# GEMM K-loops: one s_nop in front of the barrier of each misaligned compute segment so that all 128 MFMAs of every K-loop start 8-byte aligned (were 64 of 128)
# speedup vs baseline: 1.0073x; 1.0073x over previous
; #define PG8_STAGE(bufoff, gbase, voff) do { _Pragma("unroll") for (int _i = 0; _i < 2; ++_i) \
;         __builtin_amdgcn_global_load_lds((const unsigned*)((const char*)(gbase) + (voff)[_i]), (PG8_LAS unsigned*)(lds + (bufoff) + ldsw + _i * 8192), 16, 0, 0); } while (0)
; #define PG8_LDA(dst, b, h) do { _Pragma("unroll") for (int m = 0; m < 4; ++m) _Pragma("unroll") for (int k = 0; k < 2; ++k) dst[m][k] = *(const PG8_LAS bf16x8*)(lds + PG8_SA(b, h) + aoff + m * 2048 + k * 1024); } while (0)
; #define PG8_LDB(dst, b, h) do { _Pragma("unroll") for (int n = 0; n < 2; ++n) _Pragma("unroll") for (int k = 0; k < 2; ++k) dst[n][k] = *(const PG8_LAS bf16x8*)(lds + PG8_SB(b, h) + boff + n * 2048 + k * 1024); } while (0)
; #define PG8_MMA(ai, bj, At, Bt) do { __builtin_amdgcn_s_setprio(1); _Pragma("unroll") for (int m = 0; m < 4; ++m) _Pragma("unroll") for (int n = 0; n < 2; ++n) _Pragma("unroll") for (int k = 0; k < 2; ++k) \
;         acc[ai][bj][m][n] = __builtin_amdgcn_mfma_f32_16x16x32_bf16(Bt[n][k], At[m][k], acc[ai][bj][m][n], 0, 0, 0); __builtin_amdgcn_s_setprio(0); } while (0)
; #define PG8_WAIT_V(n) asm volatile("s_waitcnt vmcnt(" #n ")" ::: "memory")
; #define PG8_WAIT_L(n) asm volatile("s_waitcnt lgkmcnt(" #n ")" ::: "memory")
; template <class Epi, class Sched, bool ALIGN_EPI = false, bool SP2 = false>
; __device__ __forceinline__ void gemm_phase(PG8_LAS unsigned char* lds, const Gemm g, const Sched& S, const Epi& E) {
;     ...
;             const bool last = (t == nt - 2);
;             const char* a1 = cA + (size_t)(t + 1) * kstep;
;             const char* a2 = last ? nA : cA + (size_t)(t + 2) * kstep; const char* b2 = last ? nB : cB + (size_t)(t + 2) * kstep;
;             const char* a3 = a2 + kstep; const char* b3 = b2 + kstep;
;             if (last && has_next) S.a_ready(nxt);
;             if constexpr (SP2) {
;             PG8_LDB(B0, 0, 0); PG8_LDB(B1, 0, 1); PG8_SCHED; PG8_LDA(At, 0, 0); PG8_STAGE(PG8_SA(1, 0), a1, voffA); PG8_STAGE(PG8_SA(1, 1), a1 + hstep, voffA);
;             PG8_WAIT_V(8); PG8_WAIT_L(0); PG8_BAR; PG8_MMA(0, 0, At, B0); PG8_MMA(0, 1, At, B1); PG8_BAR; PG8_SCHED;
;             PG8_LDA(At, 0, 1); PG8_STAGE(PG8_SB(0, 0), b2, voffB); PG8_STAGE(PG8_SB(0, 1), b2 + hstep, voffB);
;             PG8_WAIT_V(6); PG8_WAIT_L(0); PG8_BAR; PG8_MMA(1, 0, At, B0); PG8_MMA(1, 1, At, B1); PG8_BAR; PG8_SCHED;
.LBB0_212:
	s_add_u32 s16, s8, s10
	s_addc_u32 s17, s9, s11
	s_add_u32 s44, s16, 0x100
	s_addc_u32 s45, s17, 0
	s_add_u32 s16, s73, s10
	s_addc_u32 s17, vcc_hi, s11
	s_add_i32 s53, 0, 0x10000
	s_cmpk_eq_i32 s10, 0xf00
	s_cselect_b32 s17, s70, s17
	s_cselect_b32 s16, s71, s16
	s_cselect_b32 s45, s89, s45
	s_cselect_b32 s44, vcc_lo, s44
	s_add_i32 s92, 0, 0x14000
	v_add_u32_e32 v158, s53, v147
	v_add_u32_e32 v174, s92, v147
	ds_read_b128 v[142:145], v158
	ds_read_b128 v[150:153], v158 offset:1024
	ds_read_b128 v[154:157], v158 offset:2048
	ds_read_b128 v[158:161], v158 offset:3072
	ds_read_b128 v[162:165], v174
	ds_read_b128 v[166:169], v174 offset:1024
	ds_read_b128 v[170:173], v174 offset:2048
	ds_read_b128 v[174:177], v174 offset:3072
	v_lshl_add_u64 v[202:203], v[138:139], 0, s[10:11]
	v_lshl_add_u64 v[206:207], v[202:203], 0, s[26:27]
	s_add_i32 m0, s97, 0x8000
	ds_read_b128 v[178:181], v149
	ds_read_b128 v[182:185], v149 offset:1024
	ds_read_b128 v[186:189], v149 offset:2048
	ds_read_b128 v[190:193], v149 offset:3072
	ds_read_b128 v[194:197], v149 offset:4096
	ds_read_b128 v[198:201], v149 offset:5120
	ds_read_b128 v[218:221], v149 offset:6144
	ds_read_b128 v[232:235], v149 offset:7168
	global_load_lds_dwordx4 v[206:207], off
	v_lshl_add_u64 v[206:207], v[140:141], 0, s[10:11]
	v_lshl_add_u64 v[208:209], v[206:207], 0, s[26:27]
	s_add_i32 m0, s97, 0xa000
	v_lshl_add_u64 v[202:203], v[202:203], 0, s[28:29]
	global_load_lds_dwordx4 v[208:209], off
	s_add_i32 m0, s97, 0xc000
	s_nop 0
	global_load_lds_dwordx4 v[202:203], off
	v_lshl_add_u64 v[202:203], v[206:207], 0, s[28:29]
	s_add_i32 m0, s97, 0xe000
	s_nop 0
	global_load_lds_dwordx4 v[202:203], off
	s_waitcnt vmcnt(8)
	s_waitcnt lgkmcnt(0)
	s_barrier
	v_mfma_f32_16x16x32_bf16 v[124:127], v[142:145], v[178:181], v[124:127]
	v_mfma_f32_16x16x32_bf16 v[120:123], v[154:157], v[178:181], v[120:123]
	v_mfma_f32_16x16x32_bf16 v[108:111], v[142:145], v[186:189], v[108:111]
	v_mfma_f32_16x16x32_bf16 v[104:107], v[154:157], v[186:189], v[104:107]
	v_mfma_f32_16x16x32_bf16 v[92:95], v[142:145], v[194:197], v[92:95]
	v_mfma_f32_16x16x32_bf16 v[88:91], v[154:157], v[194:197], v[88:91]
	v_mfma_f32_16x16x32_bf16 v[76:79], v[142:145], v[218:221], v[76:79]
	v_mfma_f32_16x16x32_bf16 v[72:75], v[154:157], v[218:221], v[72:75]
	v_mfma_f32_16x16x32_bf16 v[124:127], v[150:153], v[182:185], v[124:127]
	v_mfma_f32_16x16x32_bf16 v[120:123], v[158:161], v[182:185], v[120:123]
	v_mfma_f32_16x16x32_bf16 v[108:111], v[150:153], v[190:193], v[108:111]
	v_mfma_f32_16x16x32_bf16 v[104:107], v[158:161], v[190:193], v[104:107]
	v_mfma_f32_16x16x32_bf16 v[92:95], v[150:153], v[198:201], v[92:95]
	v_mfma_f32_16x16x32_bf16 v[88:91], v[158:161], v[198:201], v[88:91]
	v_mfma_f32_16x16x32_bf16 v[76:79], v[150:153], v[232:235], v[76:79]
	v_mfma_f32_16x16x32_bf16 v[72:75], v[158:161], v[232:235], v[72:75]
	v_mfma_f32_16x16x32_bf16 v[116:119], v[162:165], v[178:181], v[116:119]
	v_mfma_f32_16x16x32_bf16 v[112:115], v[170:173], v[178:181], v[112:115]
	v_mfma_f32_16x16x32_bf16 v[100:103], v[162:165], v[186:189], v[100:103]
	v_mfma_f32_16x16x32_bf16 v[96:99], v[170:173], v[186:189], v[96:99]
	v_mfma_f32_16x16x32_bf16 v[84:87], v[162:165], v[194:197], v[84:87]
	v_mfma_f32_16x16x32_bf16 v[80:83], v[170:173], v[194:197], v[80:83]
	v_mfma_f32_16x16x32_bf16 v[68:71], v[162:165], v[218:221], v[68:71]
	v_mfma_f32_16x16x32_bf16 v[64:67], v[170:173], v[218:221], v[64:67]
	v_mfma_f32_16x16x32_bf16 v[116:119], v[166:169], v[182:185], v[116:119]
	v_mfma_f32_16x16x32_bf16 v[112:115], v[174:177], v[182:185], v[112:115]
	v_mfma_f32_16x16x32_bf16 v[100:103], v[166:169], v[190:193], v[100:103]
	v_mfma_f32_16x16x32_bf16 v[96:99], v[174:177], v[190:193], v[96:99]
	v_mfma_f32_16x16x32_bf16 v[84:87], v[166:169], v[198:201], v[84:87]
	v_mfma_f32_16x16x32_bf16 v[80:83], v[174:177], v[198:201], v[80:83]
	v_mfma_f32_16x16x32_bf16 v[68:71], v[166:169], v[232:235], v[68:71]
	v_mfma_f32_16x16x32_bf16 v[64:67], v[174:177], v[232:235], v[64:67]
	s_barrier
	s_add_i32 s53, s53, s23
	v_lshl_add_u64 v[202:203], s[16:17], 0, v[204:205]
	s_mov_b32 m0, s53
	ds_read_b128 v[178:181], v149 offset:16384
	ds_read_b128 v[182:185], v149 offset:17408
	ds_read_b128 v[186:189], v149 offset:18432
	ds_read_b128 v[190:193], v149 offset:19456
	ds_read_b128 v[194:197], v149 offset:20480
	ds_read_b128 v[198:201], v149 offset:21504
	ds_read_b128 v[218:221], v149 offset:22528
	ds_read_b128 v[232:235], v149 offset:23552
	global_load_lds_dwordx4 v[202:203], off
	s_add_i32 m0, s53, 0x2000
	s_add_u32 s78, s16, 0x80000
	v_lshl_add_u64 v[206:207], s[16:17], 0, v[128:129]
	s_addc_u32 s79, s17, 0
	s_add_i32 s53, s92, s23
	global_load_lds_dwordx4 v[206:207], off
	v_lshl_add_u64 v[208:209], s[78:79], 0, v[204:205]
	s_mov_b32 m0, s53
	s_nop 0
	global_load_lds_dwordx4 v[208:209], off
	v_lshl_add_u64 v[208:209], s[78:79], 0, v[128:129]
	s_add_i32 m0, s53, 0x2000
	s_nop 0
	global_load_lds_dwordx4 v[208:209], off
	s_waitcnt vmcnt(6)
	s_waitcnt lgkmcnt(0)
	s_nop 0
	s_barrier
; #define PG8_MMA(ai, bj, At, Bt) do { __builtin_amdgcn_s_setprio(1); _Pragma("unroll") for (int m = 0; m < 4; ++m) _Pragma("unroll") for (int n = 0; n < 2; ++n) _Pragma("unroll") for (int k = 0; k < 2; ++k) \
;         acc[ai][bj][m][n] = __builtin_amdgcn_mfma_f32_16x16x32_bf16(Bt[n][k], At[m][k], acc[ai][bj][m][n], 0, 0, 0); __builtin_amdgcn_s_setprio(0); } while (0)
; #define PG8_WAIT_V(n) asm volatile("s_waitcnt vmcnt(" #n ")" ::: "memory")
; #define PG8_WAIT_L(n) asm volatile("s_waitcnt lgkmcnt(" #n ")" ::: "memory")
; #define PG8_BAR __builtin_amdgcn_s_barrier()
; #define PG8_SCHED __builtin_amdgcn_sched_barrier(0)
; template <class Epi, class Sched, bool ALIGN_EPI = false, bool SP2 = false>
; __device__ __forceinline__ void gemm_phase(PG8_LAS unsigned char* lds, const Gemm g, const Sched& S, const Epi& E) {
;     ...
;             PG8_WAIT_V(6); PG8_WAIT_L(0); PG8_BAR; PG8_MMA(1, 0, At, B0); PG8_MMA(1, 1, At, B1); PG8_BAR; PG8_SCHED;
	v_mfma_f32_16x16x32_bf16 v[60:63], v[142:145], v[178:181], v[60:63]
	v_mfma_f32_16x16x32_bf16 v[56:59], v[154:157], v[178:181], v[56:59]
	v_mfma_f32_16x16x32_bf16 v[44:47], v[142:145], v[186:189], v[44:47]
	v_mfma_f32_16x16x32_bf16 v[40:43], v[154:157], v[186:189], v[40:43]
	v_mfma_f32_16x16x32_bf16 v[28:31], v[142:145], v[194:197], v[28:31]
	v_mfma_f32_16x16x32_bf16 v[24:27], v[154:157], v[194:197], v[24:27]
	v_mfma_f32_16x16x32_bf16 v[12:15], v[142:145], v[218:221], v[12:15]
	v_mfma_f32_16x16x32_bf16 v[8:11], v[154:157], v[218:221], v[8:11]
	v_mfma_f32_16x16x32_bf16 v[60:63], v[150:153], v[182:185], v[60:63]
	v_mfma_f32_16x16x32_bf16 v[56:59], v[158:161], v[182:185], v[56:59]
	v_mfma_f32_16x16x32_bf16 v[44:47], v[150:153], v[190:193], v[44:47]
	v_mfma_f32_16x16x32_bf16 v[40:43], v[158:161], v[190:193], v[40:43]
	v_mfma_f32_16x16x32_bf16 v[28:31], v[150:153], v[198:201], v[28:31]
	v_mfma_f32_16x16x32_bf16 v[24:27], v[158:161], v[198:201], v[24:27]
	v_mfma_f32_16x16x32_bf16 v[12:15], v[150:153], v[232:235], v[12:15]
	v_mfma_f32_16x16x32_bf16 v[8:11], v[158:161], v[232:235], v[8:11]
	v_mfma_f32_16x16x32_bf16 v[52:55], v[162:165], v[178:181], v[52:55]
	v_mfma_f32_16x16x32_bf16 v[48:51], v[170:173], v[178:181], v[48:51]
	v_mfma_f32_16x16x32_bf16 v[36:39], v[162:165], v[186:189], v[36:39]
	v_mfma_f32_16x16x32_bf16 v[32:35], v[170:173], v[186:189], v[32:35]
	v_mfma_f32_16x16x32_bf16 v[20:23], v[162:165], v[194:197], v[20:23]
	v_mfma_f32_16x16x32_bf16 v[16:19], v[170:173], v[194:197], v[16:19]
	v_mfma_f32_16x16x32_bf16 v[4:7], v[162:165], v[218:221], v[4:7]
	v_mfma_f32_16x16x32_bf16 v[0:3], v[170:173], v[218:221], v[0:3]
	v_mfma_f32_16x16x32_bf16 v[52:55], v[166:169], v[182:185], v[52:55]
	v_mfma_f32_16x16x32_bf16 v[48:51], v[174:177], v[182:185], v[48:51]
	v_mfma_f32_16x16x32_bf16 v[36:39], v[166:169], v[190:193], v[36:39]
	v_mfma_f32_16x16x32_bf16 v[32:35], v[174:177], v[190:193], v[32:35]
	v_mfma_f32_16x16x32_bf16 v[20:23], v[166:169], v[198:201], v[20:23]
	v_mfma_f32_16x16x32_bf16 v[16:19], v[174:177], v[198:201], v[16:19]
	v_mfma_f32_16x16x32_bf16 v[4:7], v[166:169], v[232:235], v[4:7]
	v_mfma_f32_16x16x32_bf16 v[0:3], v[174:177], v[232:235], v[0:3]
	s_barrier
; #define PG8_STAGE(bufoff, gbase, voff) do { _Pragma("unroll") for (int _i = 0; _i < 2; ++_i) \
;         __builtin_amdgcn_global_load_lds((const unsigned*)((const char*)(gbase) + (voff)[_i]), (PG8_LAS unsigned*)(lds + (bufoff) + ldsw + _i * 8192), 16, 0, 0); } while (0)
; #define PG8_LDA(dst, b, h) do { _Pragma("unroll") for (int m = 0; m < 4; ++m) _Pragma("unroll") for (int k = 0; k < 2; ++k) dst[m][k] = *(const PG8_LAS bf16x8*)(lds + PG8_SA(b, h) + aoff + m * 2048 + k * 1024); } while (0)
; #define PG8_LDB(dst, b, h) do { _Pragma("unroll") for (int n = 0; n < 2; ++n) _Pragma("unroll") for (int k = 0; k < 2; ++k) dst[n][k] = *(const PG8_LAS bf16x8*)(lds + PG8_SB(b, h) + boff + n * 2048 + k * 1024); } while (0)
; #define PG8_MMA(ai, bj, At, Bt) do { __builtin_amdgcn_s_setprio(1); _Pragma("unroll") for (int m = 0; m < 4; ++m) _Pragma("unroll") for (int n = 0; n < 2; ++n) _Pragma("unroll") for (int k = 0; k < 2; ++k) \
;         acc[ai][bj][m][n] = __builtin_amdgcn_mfma_f32_16x16x32_bf16(Bt[n][k], At[m][k], acc[ai][bj][m][n], 0, 0, 0); __builtin_amdgcn_s_setprio(0); } while (0)
; #define PG8_WAIT_V(n) asm volatile("s_waitcnt vmcnt(" #n ")" ::: "memory")
; #define PG8_WAIT_L(n) asm volatile("s_waitcnt lgkmcnt(" #n ")" ::: "memory")
; #define PG8_BAR __builtin_amdgcn_s_barrier()
; #define PG8_SCHED __builtin_amdgcn_sched_barrier(0)
; template <class Epi, class Sched, bool ALIGN_EPI = false, bool SP2 = false>
; __device__ __forceinline__ void gemm_phase(PG8_LAS unsigned char* lds, const Gemm g, const Sched& S, const Epi& E) {
;     ...
;             PG8_LDB(B0, 1, 0); PG8_LDB(B1, 1, 1); PG8_SCHED; PG8_LDA(At, 1, 0); PG8_STAGE(PG8_SA(0, 0), a2, voffA); PG8_STAGE(PG8_SA(0, 1), a2 + hstep, voffA);
;             PG8_WAIT_V(8); PG8_WAIT_L(0); PG8_BAR; PG8_MMA(0, 0, At, B0); PG8_MMA(0, 1, At, B1); PG8_BAR; PG8_SCHED;
;             PG8_LDA(At, 1, 1); PG8_STAGE(PG8_SB(1, 0), b3, voffB); PG8_STAGE(PG8_SB(1, 1), b3 + hstep, voffB); (void)a3;
;             PG8_WAIT_V(6); PG8_WAIT_L(0); PG8_BAR; PG8_MMA(1, 0, At, B0); PG8_MMA(1, 1, At, B1); PG8_BAR; PG8_SCHED;
.Lpl_qk:
	s_add_i32 s53, 0, 0x18000
	s_add_i32 s78, 0, 0x1c000
	v_add_u32_e32 v158, s53, v147
	v_add_u32_e32 v174, s78, v147
	ds_read_b128 v[142:145], v158
	ds_read_b128 v[150:153], v158 offset:1024
	ds_read_b128 v[154:157], v158 offset:2048
	ds_read_b128 v[158:161], v158 offset:3072
	ds_read_b128 v[162:165], v174
	ds_read_b128 v[166:169], v174 offset:1024
	ds_read_b128 v[170:173], v174 offset:2048
	ds_read_b128 v[174:177], v174 offset:3072
	s_mov_b32 m0, s97
	v_lshl_add_u64 v[208:209], s[44:45], 0, v[132:133]
	ds_read_b128 v[178:181], v149 offset:32768
	ds_read_b128 v[182:185], v149 offset:33792
	ds_read_b128 v[186:189], v149 offset:34816
	ds_read_b128 v[190:193], v149 offset:35840
	ds_read_b128 v[194:197], v149 offset:36864
	ds_read_b128 v[198:201], v149 offset:37888
	ds_read_b128 v[218:221], v149 offset:38912
	ds_read_b128 v[232:235], v149 offset:39936
	global_load_lds_dwordx4 v[208:209], off
	v_lshl_add_u64 v[208:209], s[44:45], 0, v[130:131]
	s_add_u32 s44, s44, 0x80000
	s_mov_b32 m0, s20
	s_addc_u32 s45, s45, 0
	global_load_lds_dwordx4 v[208:209], off
	v_lshl_add_u64 v[208:209], s[44:45], 0, v[132:133]
	s_mov_b32 m0, s21
	s_nop 0
	global_load_lds_dwordx4 v[208:209], off
	v_lshl_add_u64 v[208:209], s[44:45], 0, v[130:131]
	s_mov_b32 m0, s57
	s_nop 0
	global_load_lds_dwordx4 v[208:209], off
	s_waitcnt vmcnt(8)
	s_waitcnt lgkmcnt(0)
	s_nop 0
	s_barrier
	v_mfma_f32_16x16x32_bf16 v[124:127], v[142:145], v[178:181], v[124:127]
	v_mfma_f32_16x16x32_bf16 v[120:123], v[154:157], v[178:181], v[120:123]
	v_mfma_f32_16x16x32_bf16 v[108:111], v[142:145], v[186:189], v[108:111]
	v_mfma_f32_16x16x32_bf16 v[104:107], v[154:157], v[186:189], v[104:107]
	v_mfma_f32_16x16x32_bf16 v[92:95], v[142:145], v[194:197], v[92:95]
	v_mfma_f32_16x16x32_bf16 v[88:91], v[154:157], v[194:197], v[88:91]
	v_mfma_f32_16x16x32_bf16 v[76:79], v[142:145], v[218:221], v[76:79]
	v_mfma_f32_16x16x32_bf16 v[72:75], v[154:157], v[218:221], v[72:75]
	v_mfma_f32_16x16x32_bf16 v[124:127], v[150:153], v[182:185], v[124:127]
	v_mfma_f32_16x16x32_bf16 v[120:123], v[158:161], v[182:185], v[120:123]
	v_mfma_f32_16x16x32_bf16 v[108:111], v[150:153], v[190:193], v[108:111]
	v_mfma_f32_16x16x32_bf16 v[104:107], v[158:161], v[190:193], v[104:107]
	v_mfma_f32_16x16x32_bf16 v[92:95], v[150:153], v[198:201], v[92:95]
	v_mfma_f32_16x16x32_bf16 v[88:91], v[158:161], v[198:201], v[88:91]
	v_mfma_f32_16x16x32_bf16 v[76:79], v[150:153], v[232:235], v[76:79]
	v_mfma_f32_16x16x32_bf16 v[72:75], v[158:161], v[232:235], v[72:75]
	v_mfma_f32_16x16x32_bf16 v[116:119], v[162:165], v[178:181], v[116:119]
	v_mfma_f32_16x16x32_bf16 v[112:115], v[170:173], v[178:181], v[112:115]
	v_mfma_f32_16x16x32_bf16 v[100:103], v[162:165], v[186:189], v[100:103]
	v_mfma_f32_16x16x32_bf16 v[96:99], v[170:173], v[186:189], v[96:99]
	v_mfma_f32_16x16x32_bf16 v[84:87], v[162:165], v[194:197], v[84:87]
	v_mfma_f32_16x16x32_bf16 v[80:83], v[170:173], v[194:197], v[80:83]
	v_mfma_f32_16x16x32_bf16 v[68:71], v[162:165], v[218:221], v[68:71]
	v_mfma_f32_16x16x32_bf16 v[64:67], v[170:173], v[218:221], v[64:67]
	v_mfma_f32_16x16x32_bf16 v[116:119], v[166:169], v[182:185], v[116:119]
	v_mfma_f32_16x16x32_bf16 v[112:115], v[174:177], v[182:185], v[112:115]
	v_mfma_f32_16x16x32_bf16 v[100:103], v[166:169], v[190:193], v[100:103]
	v_mfma_f32_16x16x32_bf16 v[96:99], v[174:177], v[190:193], v[96:99]
	v_mfma_f32_16x16x32_bf16 v[84:87], v[166:169], v[198:201], v[84:87]
	v_mfma_f32_16x16x32_bf16 v[80:83], v[174:177], v[198:201], v[80:83]
	v_mfma_f32_16x16x32_bf16 v[68:71], v[166:169], v[232:235], v[68:71]
	v_mfma_f32_16x16x32_bf16 v[64:67], v[174:177], v[232:235], v[64:67]
	s_barrier
	s_add_i32 s44, s53, s23
	v_lshl_add_u64 v[202:203], v[202:203], 0, s[26:27]
	s_mov_b32 m0, s44
	ds_read_b128 v[178:181], v149 offset:49152
	ds_read_b128 v[182:185], v149 offset:50176
	ds_read_b128 v[186:189], v149 offset:51200
	ds_read_b128 v[190:193], v149 offset:52224
	ds_read_b128 v[194:197], v149 offset:53248
	ds_read_b128 v[198:201], v149 offset:54272
	ds_read_b128 v[218:221], v149 offset:55296
	ds_read_b128 v[232:235], v149 offset:56320
	global_load_lds_dwordx4 v[202:203], off
	s_add_i32 m0, s44, 0x2000
	s_add_u32 s16, s16, 0x80080
	v_lshl_add_u64 v[202:203], v[206:207], 0, s[26:27]
	s_addc_u32 s17, s17, 0
	s_add_i32 s44, s78, s23
	global_load_lds_dwordx4 v[202:203], off
	v_lshl_add_u64 v[202:203], s[16:17], 0, v[204:205]
	s_mov_b32 m0, s44
	s_nop 0
	global_load_lds_dwordx4 v[202:203], off
	v_lshl_add_u64 v[202:203], s[16:17], 0, v[128:129]
	s_add_i32 m0, s44, 0x2000
	s_nop 0
	global_load_lds_dwordx4 v[202:203], off
	s_waitcnt vmcnt(6)
	s_waitcnt lgkmcnt(0)
	s_nop 0
	s_barrier
	v_mfma_f32_16x16x32_bf16 v[60:63], v[142:145], v[178:181], v[60:63]
	v_mfma_f32_16x16x32_bf16 v[56:59], v[154:157], v[178:181], v[56:59]
	v_mfma_f32_16x16x32_bf16 v[44:47], v[142:145], v[186:189], v[44:47]
	v_mfma_f32_16x16x32_bf16 v[40:43], v[154:157], v[186:189], v[40:43]
	v_mfma_f32_16x16x32_bf16 v[28:31], v[142:145], v[194:197], v[28:31]
	v_mfma_f32_16x16x32_bf16 v[24:27], v[154:157], v[194:197], v[24:27]
	v_mfma_f32_16x16x32_bf16 v[12:15], v[142:145], v[218:221], v[12:15]
	v_mfma_f32_16x16x32_bf16 v[8:11], v[154:157], v[218:221], v[8:11]
	v_mfma_f32_16x16x32_bf16 v[60:63], v[150:153], v[182:185], v[60:63]
	v_mfma_f32_16x16x32_bf16 v[56:59], v[158:161], v[182:185], v[56:59]
	v_mfma_f32_16x16x32_bf16 v[44:47], v[150:153], v[190:193], v[44:47]
	v_mfma_f32_16x16x32_bf16 v[40:43], v[158:161], v[190:193], v[40:43]
	v_mfma_f32_16x16x32_bf16 v[28:31], v[150:153], v[198:201], v[28:31]
	v_mfma_f32_16x16x32_bf16 v[24:27], v[158:161], v[198:201], v[24:27]
	v_mfma_f32_16x16x32_bf16 v[12:15], v[150:153], v[232:235], v[12:15]
	v_mfma_f32_16x16x32_bf16 v[8:11], v[158:161], v[232:235], v[8:11]
	v_mfma_f32_16x16x32_bf16 v[52:55], v[162:165], v[178:181], v[52:55]
	v_mfma_f32_16x16x32_bf16 v[48:51], v[170:173], v[178:181], v[48:51]
	v_mfma_f32_16x16x32_bf16 v[36:39], v[162:165], v[186:189], v[36:39]
	v_mfma_f32_16x16x32_bf16 v[32:35], v[170:173], v[186:189], v[32:35]
	v_mfma_f32_16x16x32_bf16 v[20:23], v[162:165], v[194:197], v[20:23]
	v_mfma_f32_16x16x32_bf16 v[16:19], v[170:173], v[194:197], v[16:19]
	v_mfma_f32_16x16x32_bf16 v[4:7], v[162:165], v[218:221], v[4:7]
	v_mfma_f32_16x16x32_bf16 v[0:3], v[170:173], v[218:221], v[0:3]
	v_mfma_f32_16x16x32_bf16 v[52:55], v[166:169], v[182:185], v[52:55]
	v_mfma_f32_16x16x32_bf16 v[48:51], v[174:177], v[182:185], v[48:51]
	v_mfma_f32_16x16x32_bf16 v[36:39], v[166:169], v[190:193], v[36:39]
	v_mfma_f32_16x16x32_bf16 v[32:35], v[174:177], v[190:193], v[32:35]
	v_mfma_f32_16x16x32_bf16 v[20:23], v[166:169], v[198:201], v[20:23]
	v_mfma_f32_16x16x32_bf16 v[16:19], v[174:177], v[198:201], v[16:19]
	v_mfma_f32_16x16x32_bf16 v[4:7], v[166:169], v[232:235], v[4:7]
	v_mfma_f32_16x16x32_bf16 v[0:3], v[174:177], v[232:235], v[0:3]
	s_barrier
	s_add_i32 s52, s52, 2
	s_add_u32 s10, s10, 0x100
	s_addc_u32 s11, s11, 0
	s_cmp_gt_u32 s52, 29
	s_cbranch_scc0 .LBB0_212
	s_and_b64 vcc, exec, s[76:77]
	s_cbranch_vccz .LBB0_215
	s_barrier

; #define PG8_STAGE(bufoff, gbase, voff) do { _Pragma("unroll") for (int _i = 0; _i < 2; ++_i) \
;         __builtin_amdgcn_global_load_lds((const unsigned*)((const char*)(gbase) + (voff)[_i]), (PG8_LAS unsigned*)(lds + (bufoff) + ldsw + _i * 8192), 16, 0, 0); } while (0)
; #define PG8_LDA(dst, b, h) do { _Pragma("unroll") for (int m = 0; m < 4; ++m) _Pragma("unroll") for (int k = 0; k < 2; ++k) dst[m][k] = *(const PG8_LAS bf16x8*)(lds + PG8_SA(b, h) + aoff + m * 2048 + k * 1024); } while (0)
; #define PG8_LDB(dst, b, h) do { _Pragma("unroll") for (int n = 0; n < 2; ++n) _Pragma("unroll") for (int k = 0; k < 2; ++k) dst[n][k] = *(const PG8_LAS bf16x8*)(lds + PG8_SB(b, h) + boff + n * 2048 + k * 1024); } while (0)
; #define PG8_MMA(ai, bj, At, Bt) do { __builtin_amdgcn_s_setprio(1); _Pragma("unroll") for (int m = 0; m < 4; ++m) _Pragma("unroll") for (int n = 0; n < 2; ++n) _Pragma("unroll") for (int k = 0; k < 2; ++k) \
;         acc[ai][bj][m][n] = __builtin_amdgcn_mfma_f32_16x16x32_bf16(Bt[n][k], At[m][k], acc[ai][bj][m][n], 0, 0, 0); __builtin_amdgcn_s_setprio(0); } while (0)
; #define PG8_WAIT_V(n) asm volatile("s_waitcnt vmcnt(" #n ")" ::: "memory")
; #define PG8_WAIT_L(n) asm volatile("s_waitcnt lgkmcnt(" #n ")" ::: "memory")
; template <class Epi, class Sched, bool ALIGN_EPI = false, bool SP2 = false>
; __device__ __forceinline__ void gemm_phase(PG8_LAS unsigned char* lds, const Gemm g, const Sched& S, const Epi& E) {
;     ...
;             const bool last = (t == nt - 2);
;             const char* a1 = cA + (size_t)(t + 1) * kstep;
;             const char* a2 = last ? nA : cA + (size_t)(t + 2) * kstep; const char* b2 = last ? nB : cB + (size_t)(t + 2) * kstep;
;             const char* a3 = a2 + kstep; const char* b3 = b2 + kstep;
;             if (last && has_next) S.a_ready(nxt);
;             if constexpr (SP2) {
;             PG8_LDB(B0, 0, 0); PG8_LDB(B1, 0, 1); PG8_SCHED; PG8_LDA(At, 0, 0); PG8_STAGE(PG8_SA(1, 0), a1, voffA); PG8_STAGE(PG8_SA(1, 1), a1 + hstep, voffA);
;             PG8_WAIT_V(8); PG8_WAIT_L(0); PG8_BAR; PG8_MMA(0, 0, At, B0); PG8_MMA(0, 1, At, B1); PG8_BAR; PG8_SCHED;
;             PG8_LDA(At, 0, 1); PG8_STAGE(PG8_SB(0, 0), b2, voffB); PG8_STAGE(PG8_SB(0, 1), b2 + hstep, voffB);
;             PG8_WAIT_V(6); PG8_WAIT_L(0); PG8_BAR; PG8_MMA(1, 0, At, B0); PG8_MMA(1, 1, At, B1); PG8_BAR; PG8_SCHED;
.LBB0_232:
	s_add_u32 s44, s16, s88
	s_addc_u32 s45, s17, s89
	s_add_u32 s53, s44, 0x100
	s_addc_u32 s78, s45, 0
	s_add_u32 s44, s70, s88
	s_addc_u32 s45, s71, s89
	s_add_i32 s79, 0, 0x10000
	s_cmpk_eq_i32 s88, 0xf00
	s_cselect_b32 s45, s11, s45
	s_cselect_b32 s44, s69, s44
	s_cselect_b32 s95, s47, s78
	s_cselect_b32 s94, s68, s53
	s_add_i32 s53, 0, 0x14000
	v_add_u32_e32 v154, s79, v161
	v_add_u32_e32 v158, s53, v161
	ds_read_b128 v[100:103], v154
	ds_read_b128 v[104:107], v154 offset:1024
	ds_read_b128 v[108:111], v154 offset:2048
	ds_read_b128 v[154:157], v154 offset:3072
	ds_read_b128 v[164:167], v158
	ds_read_b128 v[168:171], v158 offset:1024
	ds_read_b128 v[172:175], v158 offset:2048
	ds_read_b128 v[176:179], v158 offset:3072
	v_lshl_add_u64 v[158:159], v[96:97], 0, s[88:89]
	v_lshl_add_u64 v[206:207], v[158:159], 0, s[26:27]
	s_add_i32 m0, s57, 0x8000
	ds_read_b128 v[180:183], v163
	ds_read_b128 v[184:187], v163 offset:1024
	ds_read_b128 v[188:191], v163 offset:2048
	ds_read_b128 v[192:195], v163 offset:3072
	ds_read_b128 v[196:199], v163 offset:4096
	ds_read_b128 v[200:203], v163 offset:5120
	ds_read_b128 v[218:221], v163 offset:6144
	ds_read_b128 v[232:235], v163 offset:7168
	global_load_lds_dwordx4 v[206:207], off
	v_lshl_add_u64 v[206:207], v[98:99], 0, s[88:89]
	v_lshl_add_u64 v[208:209], v[206:207], 0, s[26:27]
	s_add_i32 m0, s57, 0xa000
	v_lshl_add_u64 v[158:159], v[158:159], 0, s[28:29]
	global_load_lds_dwordx4 v[208:209], off
	s_add_i32 m0, s57, 0xc000
	s_nop 0
	global_load_lds_dwordx4 v[158:159], off
	v_lshl_add_u64 v[158:159], v[206:207], 0, s[28:29]
	s_add_i32 m0, s57, 0xe000
	s_nop 0
	global_load_lds_dwordx4 v[158:159], off
	s_waitcnt vmcnt(8)
	s_waitcnt lgkmcnt(0)
	s_nop 0
	s_barrier
	v_mfma_f32_16x16x32_bf16 v[140:143], v[100:103], v[180:183], v[140:143]
	v_mfma_f32_16x16x32_bf16 v[136:139], v[108:111], v[180:183], v[136:139]
	v_mfma_f32_16x16x32_bf16 v[124:127], v[100:103], v[188:191], v[124:127]
	v_mfma_f32_16x16x32_bf16 v[120:123], v[108:111], v[188:191], v[120:123]
	v_mfma_f32_16x16x32_bf16 v[92:95], v[100:103], v[196:199], v[92:95]
	v_mfma_f32_16x16x32_bf16 v[88:91], v[108:111], v[196:199], v[88:91]
	v_mfma_f32_16x16x32_bf16 v[76:79], v[100:103], v[218:221], v[76:79]
	v_mfma_f32_16x16x32_bf16 v[72:75], v[108:111], v[218:221], v[72:75]
	v_mfma_f32_16x16x32_bf16 v[140:143], v[104:107], v[184:187], v[140:143]
	v_mfma_f32_16x16x32_bf16 v[136:139], v[154:157], v[184:187], v[136:139]
	v_mfma_f32_16x16x32_bf16 v[124:127], v[104:107], v[192:195], v[124:127]
	v_mfma_f32_16x16x32_bf16 v[120:123], v[154:157], v[192:195], v[120:123]
	v_mfma_f32_16x16x32_bf16 v[92:95], v[104:107], v[200:203], v[92:95]
	v_mfma_f32_16x16x32_bf16 v[88:91], v[154:157], v[200:203], v[88:91]
	v_mfma_f32_16x16x32_bf16 v[76:79], v[104:107], v[232:235], v[76:79]
	v_mfma_f32_16x16x32_bf16 v[72:75], v[154:157], v[232:235], v[72:75]
	v_mfma_f32_16x16x32_bf16 v[132:135], v[164:167], v[180:183], v[132:135]
	v_mfma_f32_16x16x32_bf16 v[128:131], v[172:175], v[180:183], v[128:131]
	v_mfma_f32_16x16x32_bf16 v[116:119], v[164:167], v[188:191], v[116:119]
	v_mfma_f32_16x16x32_bf16 v[112:115], v[172:175], v[188:191], v[112:115]
	v_mfma_f32_16x16x32_bf16 v[84:87], v[164:167], v[196:199], v[84:87]
	v_mfma_f32_16x16x32_bf16 v[80:83], v[172:175], v[196:199], v[80:83]
	v_mfma_f32_16x16x32_bf16 v[68:71], v[164:167], v[218:221], v[68:71]
	v_mfma_f32_16x16x32_bf16 v[64:67], v[172:175], v[218:221], v[64:67]
	v_mfma_f32_16x16x32_bf16 v[132:135], v[168:171], v[184:187], v[132:135]
	v_mfma_f32_16x16x32_bf16 v[128:131], v[176:179], v[184:187], v[128:131]
	v_mfma_f32_16x16x32_bf16 v[116:119], v[168:171], v[192:195], v[116:119]
	v_mfma_f32_16x16x32_bf16 v[112:115], v[176:179], v[192:195], v[112:115]
	v_mfma_f32_16x16x32_bf16 v[84:87], v[168:171], v[200:203], v[84:87]
	v_mfma_f32_16x16x32_bf16 v[80:83], v[176:179], v[200:203], v[80:83]
	v_mfma_f32_16x16x32_bf16 v[68:71], v[168:171], v[232:235], v[68:71]
	v_mfma_f32_16x16x32_bf16 v[64:67], v[176:179], v[232:235], v[64:67]
	s_barrier
	s_add_i32 s78, s79, s23
	v_lshl_add_u64 v[158:159], s[44:45], 0, v[204:205]
	s_mov_b32 m0, s78
	ds_read_b128 v[180:183], v163 offset:16384
	ds_read_b128 v[184:187], v163 offset:17408
	ds_read_b128 v[188:191], v163 offset:18432
	ds_read_b128 v[192:195], v163 offset:19456
	ds_read_b128 v[196:199], v163 offset:20480
	ds_read_b128 v[200:203], v163 offset:21504
	ds_read_b128 v[218:221], v163 offset:22528
	ds_read_b128 v[232:235], v163 offset:23552
	global_load_lds_dwordx4 v[158:159], off
	s_add_i32 m0, s78, 0x2000
	s_add_u32 s78, s44, 0x80000
	v_lshl_add_u64 v[206:207], s[44:45], 0, v[144:145]
	s_addc_u32 s79, s45, 0
	s_add_i32 s53, s53, s23
	global_load_lds_dwordx4 v[206:207], off
	v_lshl_add_u64 v[208:209], s[78:79], 0, v[204:205]
	s_mov_b32 m0, s53
	s_nop 0
	global_load_lds_dwordx4 v[208:209], off
	v_lshl_add_u64 v[208:209], s[78:79], 0, v[144:145]
	s_add_i32 m0, s53, 0x2000
	s_nop 0
	global_load_lds_dwordx4 v[208:209], off
	s_waitcnt vmcnt(6)
	s_waitcnt lgkmcnt(0)
	s_nop 0
	s_barrier
; #define PG8_MMA(ai, bj, At, Bt) do { __builtin_amdgcn_s_setprio(1); _Pragma("unroll") for (int m = 0; m < 4; ++m) _Pragma("unroll") for (int n = 0; n < 2; ++n) _Pragma("unroll") for (int k = 0; k < 2; ++k) \
;         acc[ai][bj][m][n] = __builtin_amdgcn_mfma_f32_16x16x32_bf16(Bt[n][k], At[m][k], acc[ai][bj][m][n], 0, 0, 0); __builtin_amdgcn_s_setprio(0); } while (0)
; #define PG8_WAIT_V(n) asm volatile("s_waitcnt vmcnt(" #n ")" ::: "memory")
; #define PG8_WAIT_L(n) asm volatile("s_waitcnt lgkmcnt(" #n ")" ::: "memory")
; #define PG8_BAR __builtin_amdgcn_s_barrier()
; #define PG8_SCHED __builtin_amdgcn_sched_barrier(0)
; template <class Epi, class Sched, bool ALIGN_EPI = false, bool SP2 = false>
; __device__ __forceinline__ void gemm_phase(PG8_LAS unsigned char* lds, const Gemm g, const Sched& S, const Epi& E) {
;     ...
;             PG8_WAIT_V(6); PG8_WAIT_L(0); PG8_BAR; PG8_MMA(1, 0, At, B0); PG8_MMA(1, 1, At, B1); PG8_BAR; PG8_SCHED;
	v_mfma_f32_16x16x32_bf16 v[60:63], v[100:103], v[180:183], v[60:63]
	v_mfma_f32_16x16x32_bf16 v[56:59], v[108:111], v[180:183], v[56:59]
	v_mfma_f32_16x16x32_bf16 v[48:51], v[100:103], v[188:191], v[48:51]
	v_mfma_f32_16x16x32_bf16 v[40:43], v[108:111], v[188:191], v[40:43]
	v_mfma_f32_16x16x32_bf16 v[32:35], v[100:103], v[196:199], v[32:35]
	v_mfma_f32_16x16x32_bf16 v[24:27], v[108:111], v[196:199], v[24:27]
	v_mfma_f32_16x16x32_bf16 v[16:19], v[100:103], v[218:221], v[16:19]
	v_mfma_f32_16x16x32_bf16 v[8:11], v[108:111], v[218:221], v[8:11]
	v_mfma_f32_16x16x32_bf16 v[60:63], v[104:107], v[184:187], v[60:63]
	v_mfma_f32_16x16x32_bf16 v[56:59], v[154:157], v[184:187], v[56:59]
	v_mfma_f32_16x16x32_bf16 v[48:51], v[104:107], v[192:195], v[48:51]
	v_mfma_f32_16x16x32_bf16 v[40:43], v[154:157], v[192:195], v[40:43]
	v_mfma_f32_16x16x32_bf16 v[32:35], v[104:107], v[200:203], v[32:35]
	v_mfma_f32_16x16x32_bf16 v[24:27], v[154:157], v[200:203], v[24:27]
	v_mfma_f32_16x16x32_bf16 v[16:19], v[104:107], v[232:235], v[16:19]
	v_mfma_f32_16x16x32_bf16 v[8:11], v[154:157], v[232:235], v[8:11]
	v_mfma_f32_16x16x32_bf16 v[52:55], v[164:167], v[180:183], v[52:55]
	v_mfma_f32_16x16x32_bf16 v[44:47], v[172:175], v[180:183], v[44:47]
	v_mfma_f32_16x16x32_bf16 v[36:39], v[164:167], v[188:191], v[36:39]
	v_mfma_f32_16x16x32_bf16 v[28:31], v[172:175], v[188:191], v[28:31]
	v_mfma_f32_16x16x32_bf16 v[20:23], v[164:167], v[196:199], v[20:23]
	v_mfma_f32_16x16x32_bf16 v[12:15], v[172:175], v[196:199], v[12:15]
	v_mfma_f32_16x16x32_bf16 v[4:7], v[164:167], v[218:221], v[4:7]
	v_mfma_f32_16x16x32_bf16 v[0:3], v[172:175], v[218:221], v[0:3]
	v_mfma_f32_16x16x32_bf16 v[52:55], v[168:171], v[184:187], v[52:55]
	v_mfma_f32_16x16x32_bf16 v[44:47], v[176:179], v[184:187], v[44:47]
	v_mfma_f32_16x16x32_bf16 v[36:39], v[168:171], v[192:195], v[36:39]
	v_mfma_f32_16x16x32_bf16 v[28:31], v[176:179], v[192:195], v[28:31]
	v_mfma_f32_16x16x32_bf16 v[20:23], v[168:171], v[200:203], v[20:23]
	v_mfma_f32_16x16x32_bf16 v[12:15], v[176:179], v[200:203], v[12:15]
	v_mfma_f32_16x16x32_bf16 v[4:7], v[168:171], v[232:235], v[4:7]
	v_mfma_f32_16x16x32_bf16 v[0:3], v[176:179], v[232:235], v[0:3]
	s_barrier
; #define PG8_STAGE(bufoff, gbase, voff) do { _Pragma("unroll") for (int _i = 0; _i < 2; ++_i) \
;         __builtin_amdgcn_global_load_lds((const unsigned*)((const char*)(gbase) + (voff)[_i]), (PG8_LAS unsigned*)(lds + (bufoff) + ldsw + _i * 8192), 16, 0, 0); } while (0)
; #define PG8_LDA(dst, b, h) do { _Pragma("unroll") for (int m = 0; m < 4; ++m) _Pragma("unroll") for (int k = 0; k < 2; ++k) dst[m][k] = *(const PG8_LAS bf16x8*)(lds + PG8_SA(b, h) + aoff + m * 2048 + k * 1024); } while (0)
; #define PG8_LDB(dst, b, h) do { _Pragma("unroll") for (int n = 0; n < 2; ++n) _Pragma("unroll") for (int k = 0; k < 2; ++k) dst[n][k] = *(const PG8_LAS bf16x8*)(lds + PG8_SB(b, h) + boff + n * 2048 + k * 1024); } while (0)
; #define PG8_MMA(ai, bj, At, Bt) do { __builtin_amdgcn_s_setprio(1); _Pragma("unroll") for (int m = 0; m < 4; ++m) _Pragma("unroll") for (int n = 0; n < 2; ++n) _Pragma("unroll") for (int k = 0; k < 2; ++k) \
;         acc[ai][bj][m][n] = __builtin_amdgcn_mfma_f32_16x16x32_bf16(Bt[n][k], At[m][k], acc[ai][bj][m][n], 0, 0, 0); __builtin_amdgcn_s_setprio(0); } while (0)
; #define PG8_WAIT_V(n) asm volatile("s_waitcnt vmcnt(" #n ")" ::: "memory")
; #define PG8_WAIT_L(n) asm volatile("s_waitcnt lgkmcnt(" #n ")" ::: "memory")
; #define PG8_BAR __builtin_amdgcn_s_barrier()
; #define PG8_SCHED __builtin_amdgcn_sched_barrier(0)
; template <class Epi, class Sched, bool ALIGN_EPI = false, bool SP2 = false>
; __device__ __forceinline__ void gemm_phase(PG8_LAS unsigned char* lds, const Gemm g, const Sched& S, const Epi& E) {
;     ...
;             PG8_LDB(B0, 1, 0); PG8_LDB(B1, 1, 1); PG8_SCHED; PG8_LDA(At, 1, 0); PG8_STAGE(PG8_SA(0, 0), a2, voffA); PG8_STAGE(PG8_SA(0, 1), a2 + hstep, voffA);
;             PG8_WAIT_V(8); PG8_WAIT_L(0); PG8_BAR; PG8_MMA(0, 0, At, B0); PG8_MMA(0, 1, At, B1); PG8_BAR; PG8_SCHED;
;             PG8_LDA(At, 1, 1); PG8_STAGE(PG8_SB(1, 0), b3, voffB); PG8_STAGE(PG8_SB(1, 1), b3 + hstep, voffB); (void)a3;
;             PG8_WAIT_V(6); PG8_WAIT_L(0); PG8_BAR; PG8_MMA(1, 0, At, B0); PG8_MMA(1, 1, At, B1); PG8_BAR; PG8_SCHED;
.Lpl_vt:
	s_add_i32 s53, 0, 0x18000
	s_add_i32 s92, 0, 0x1c000
	v_add_u32_e32 v154, s53, v161
	v_add_u32_e32 v176, s92, v161
	ds_read_b128 v[100:103], v154
	ds_read_b128 v[104:107], v154 offset:1024
	ds_read_b128 v[108:111], v154 offset:2048
	ds_read_b128 v[154:157], v154 offset:3072
	ds_read_b128 v[164:167], v176
	ds_read_b128 v[168:171], v176 offset:1024
	ds_read_b128 v[172:175], v176 offset:2048
	ds_read_b128 v[176:179], v176 offset:3072
	s_mov_b32 m0, s57
	v_lshl_add_u64 v[208:209], s[94:95], 0, v[148:149]
	s_add_u32 s78, s94, 0x80000
	ds_read_b128 v[180:183], v163 offset:32768
	ds_read_b128 v[184:187], v163 offset:33792
	ds_read_b128 v[188:191], v163 offset:34816
	ds_read_b128 v[192:195], v163 offset:35840
	ds_read_b128 v[196:199], v163 offset:36864
	ds_read_b128 v[200:203], v163 offset:37888
	ds_read_b128 v[218:221], v163 offset:38912
	ds_read_b128 v[232:235], v163 offset:39936
	global_load_lds_dwordx4 v[208:209], off
	v_lshl_add_u64 v[208:209], s[94:95], 0, v[146:147]
	s_mov_b32 m0, s84
	s_addc_u32 s79, s95, 0
	global_load_lds_dwordx4 v[208:209], off
	v_lshl_add_u64 v[208:209], s[78:79], 0, v[148:149]
	s_mov_b32 m0, s97
	s_nop 0
	global_load_lds_dwordx4 v[208:209], off
	v_lshl_add_u64 v[208:209], s[78:79], 0, v[146:147]
	s_mov_b32 m0, s34
	s_nop 0
	global_load_lds_dwordx4 v[208:209], off
	s_waitcnt vmcnt(8)
	s_waitcnt lgkmcnt(0)
	s_nop 0
	s_barrier
	v_mfma_f32_16x16x32_bf16 v[140:143], v[100:103], v[180:183], v[140:143]
	v_mfma_f32_16x16x32_bf16 v[136:139], v[108:111], v[180:183], v[136:139]
	v_mfma_f32_16x16x32_bf16 v[124:127], v[100:103], v[188:191], v[124:127]
	v_mfma_f32_16x16x32_bf16 v[120:123], v[108:111], v[188:191], v[120:123]
	v_mfma_f32_16x16x32_bf16 v[92:95], v[100:103], v[196:199], v[92:95]
	v_mfma_f32_16x16x32_bf16 v[88:91], v[108:111], v[196:199], v[88:91]
	v_mfma_f32_16x16x32_bf16 v[76:79], v[100:103], v[218:221], v[76:79]
	v_mfma_f32_16x16x32_bf16 v[72:75], v[108:111], v[218:221], v[72:75]
	v_mfma_f32_16x16x32_bf16 v[140:143], v[104:107], v[184:187], v[140:143]
	v_mfma_f32_16x16x32_bf16 v[136:139], v[154:157], v[184:187], v[136:139]
	v_mfma_f32_16x16x32_bf16 v[124:127], v[104:107], v[192:195], v[124:127]
	v_mfma_f32_16x16x32_bf16 v[120:123], v[154:157], v[192:195], v[120:123]
	v_mfma_f32_16x16x32_bf16 v[92:95], v[104:107], v[200:203], v[92:95]
	v_mfma_f32_16x16x32_bf16 v[88:91], v[154:157], v[200:203], v[88:91]
	v_mfma_f32_16x16x32_bf16 v[76:79], v[104:107], v[232:235], v[76:79]
	v_mfma_f32_16x16x32_bf16 v[72:75], v[154:157], v[232:235], v[72:75]
	v_mfma_f32_16x16x32_bf16 v[132:135], v[164:167], v[180:183], v[132:135]
	v_mfma_f32_16x16x32_bf16 v[128:131], v[172:175], v[180:183], v[128:131]
	v_mfma_f32_16x16x32_bf16 v[116:119], v[164:167], v[188:191], v[116:119]
	v_mfma_f32_16x16x32_bf16 v[112:115], v[172:175], v[188:191], v[112:115]
	v_mfma_f32_16x16x32_bf16 v[84:87], v[164:167], v[196:199], v[84:87]
	v_mfma_f32_16x16x32_bf16 v[80:83], v[172:175], v[196:199], v[80:83]
	v_mfma_f32_16x16x32_bf16 v[68:71], v[164:167], v[218:221], v[68:71]
	v_mfma_f32_16x16x32_bf16 v[64:67], v[172:175], v[218:221], v[64:67]
	v_mfma_f32_16x16x32_bf16 v[132:135], v[168:171], v[184:187], v[132:135]
	v_mfma_f32_16x16x32_bf16 v[128:131], v[176:179], v[184:187], v[128:131]
	v_mfma_f32_16x16x32_bf16 v[116:119], v[168:171], v[192:195], v[116:119]
	v_mfma_f32_16x16x32_bf16 v[112:115], v[176:179], v[192:195], v[112:115]
	v_mfma_f32_16x16x32_bf16 v[84:87], v[168:171], v[200:203], v[84:87]
	v_mfma_f32_16x16x32_bf16 v[80:83], v[176:179], v[200:203], v[80:83]
	v_mfma_f32_16x16x32_bf16 v[68:71], v[168:171], v[232:235], v[68:71]
	v_mfma_f32_16x16x32_bf16 v[64:67], v[176:179], v[232:235], v[64:67]
	s_barrier
	s_add_i32 s53, s53, s23
	v_lshl_add_u64 v[158:159], v[158:159], 0, s[26:27]
	s_mov_b32 m0, s53
	ds_read_b128 v[180:183], v163 offset:49152
	ds_read_b128 v[184:187], v163 offset:50176
	ds_read_b128 v[188:191], v163 offset:51200
	ds_read_b128 v[192:195], v163 offset:52224
	ds_read_b128 v[196:199], v163 offset:53248
	ds_read_b128 v[200:203], v163 offset:54272
	ds_read_b128 v[218:221], v163 offset:55296
	ds_read_b128 v[232:235], v163 offset:56320
	global_load_lds_dwordx4 v[158:159], off
	s_add_i32 m0, s53, 0x2000
	s_add_u32 s44, s44, 0x80080
	v_lshl_add_u64 v[158:159], v[206:207], 0, s[26:27]
	s_addc_u32 s45, s45, 0
	s_add_i32 s53, s92, s23
	global_load_lds_dwordx4 v[158:159], off
	v_lshl_add_u64 v[158:159], s[44:45], 0, v[204:205]
	s_mov_b32 m0, s53
	s_nop 0
	global_load_lds_dwordx4 v[158:159], off
	v_lshl_add_u64 v[158:159], s[44:45], 0, v[144:145]
	s_add_i32 m0, s53, 0x2000
	s_nop 0
	global_load_lds_dwordx4 v[158:159], off
	s_waitcnt vmcnt(6)
	s_waitcnt lgkmcnt(0)
	s_nop 0
	s_barrier
	v_mfma_f32_16x16x32_bf16 v[60:63], v[100:103], v[180:183], v[60:63]
	v_mfma_f32_16x16x32_bf16 v[56:59], v[108:111], v[180:183], v[56:59]
	v_mfma_f32_16x16x32_bf16 v[48:51], v[100:103], v[188:191], v[48:51]
	v_mfma_f32_16x16x32_bf16 v[40:43], v[108:111], v[188:191], v[40:43]
	v_mfma_f32_16x16x32_bf16 v[32:35], v[100:103], v[196:199], v[32:35]
	v_mfma_f32_16x16x32_bf16 v[24:27], v[108:111], v[196:199], v[24:27]
	v_mfma_f32_16x16x32_bf16 v[16:19], v[100:103], v[218:221], v[16:19]
	v_mfma_f32_16x16x32_bf16 v[8:11], v[108:111], v[218:221], v[8:11]
	v_mfma_f32_16x16x32_bf16 v[60:63], v[104:107], v[184:187], v[60:63]
	v_mfma_f32_16x16x32_bf16 v[56:59], v[154:157], v[184:187], v[56:59]
	v_mfma_f32_16x16x32_bf16 v[48:51], v[104:107], v[192:195], v[48:51]
	v_mfma_f32_16x16x32_bf16 v[40:43], v[154:157], v[192:195], v[40:43]
	v_mfma_f32_16x16x32_bf16 v[32:35], v[104:107], v[200:203], v[32:35]
	v_mfma_f32_16x16x32_bf16 v[24:27], v[154:157], v[200:203], v[24:27]
	v_mfma_f32_16x16x32_bf16 v[16:19], v[104:107], v[232:235], v[16:19]
	v_mfma_f32_16x16x32_bf16 v[8:11], v[154:157], v[232:235], v[8:11]
	v_mfma_f32_16x16x32_bf16 v[52:55], v[164:167], v[180:183], v[52:55]
	v_mfma_f32_16x16x32_bf16 v[44:47], v[172:175], v[180:183], v[44:47]
	v_mfma_f32_16x16x32_bf16 v[36:39], v[164:167], v[188:191], v[36:39]
	v_mfma_f32_16x16x32_bf16 v[28:31], v[172:175], v[188:191], v[28:31]
	v_mfma_f32_16x16x32_bf16 v[20:23], v[164:167], v[196:199], v[20:23]
	v_mfma_f32_16x16x32_bf16 v[12:15], v[172:175], v[196:199], v[12:15]
	v_mfma_f32_16x16x32_bf16 v[4:7], v[164:167], v[218:221], v[4:7]
	v_mfma_f32_16x16x32_bf16 v[0:3], v[172:175], v[218:221], v[0:3]
	v_mfma_f32_16x16x32_bf16 v[52:55], v[168:171], v[184:187], v[52:55]
	v_mfma_f32_16x16x32_bf16 v[44:47], v[176:179], v[184:187], v[44:47]
	v_mfma_f32_16x16x32_bf16 v[36:39], v[168:171], v[192:195], v[36:39]
	v_mfma_f32_16x16x32_bf16 v[28:31], v[176:179], v[192:195], v[28:31]
	v_mfma_f32_16x16x32_bf16 v[20:23], v[168:171], v[200:203], v[20:23]
	v_mfma_f32_16x16x32_bf16 v[12:15], v[176:179], v[200:203], v[12:15]
	v_mfma_f32_16x16x32_bf16 v[4:7], v[168:171], v[232:235], v[4:7]
	v_mfma_f32_16x16x32_bf16 v[0:3], v[176:179], v[232:235], v[0:3]
	s_barrier
	s_add_i32 s52, s52, 2
	s_add_u32 s88, s88, 0x100
	s_addc_u32 s89, s89, 0
	s_cmp_gt_u32 s52, 29
	s_cbranch_scc0 .LBB0_232
	s_and_b64 vcc, exec, s[8:9]
	s_cbranch_vccz .LBB0_235
	s_barrier

; #define PG8_STAGE(bufoff, gbase, voff) do { _Pragma("unroll") for (int _i = 0; _i < 2; ++_i) \
;         __builtin_amdgcn_global_load_lds((const unsigned*)((const char*)(gbase) + (voff)[_i]), (PG8_LAS unsigned*)(lds + (bufoff) + ldsw + _i * 8192), 16, 0, 0); } while (0)
; #define PG8_LDA(dst, b, h) do { _Pragma("unroll") for (int m = 0; m < 4; ++m) _Pragma("unroll") for (int k = 0; k < 2; ++k) dst[m][k] = *(const PG8_LAS bf16x8*)(lds + PG8_SA(b, h) + aoff + m * 2048 + k * 1024); } while (0)
; #define PG8_LDB(dst, b, h) do { _Pragma("unroll") for (int n = 0; n < 2; ++n) _Pragma("unroll") for (int k = 0; k < 2; ++k) dst[n][k] = *(const PG8_LAS bf16x8*)(lds + PG8_SB(b, h) + boff + n * 2048 + k * 1024); } while (0)
; #define PG8_MMA(ai, bj, At, Bt) do { __builtin_amdgcn_s_setprio(1); _Pragma("unroll") for (int m = 0; m < 4; ++m) _Pragma("unroll") for (int n = 0; n < 2; ++n) _Pragma("unroll") for (int k = 0; k < 2; ++k) \
;         acc[ai][bj][m][n] = __builtin_amdgcn_mfma_f32_16x16x32_bf16(Bt[n][k], At[m][k], acc[ai][bj][m][n], 0, 0, 0); __builtin_amdgcn_s_setprio(0); } while (0)
; #define PG8_WAIT_V(n) asm volatile("s_waitcnt vmcnt(" #n ")" ::: "memory")
; #define PG8_WAIT_L(n) asm volatile("s_waitcnt lgkmcnt(" #n ")" ::: "memory")
; template <class Epi, class Sched, bool ALIGN_EPI = false, bool SP2 = false>
; __device__ __forceinline__ void gemm_phase(PG8_LAS unsigned char* lds, const Gemm g, const Sched& S, const Epi& E) {
;     ...
;             const bool last = (t == nt - 2);
;             const char* a1 = cA + (size_t)(t + 1) * kstep;
;             const char* a2 = last ? nA : cA + (size_t)(t + 2) * kstep; const char* b2 = last ? nB : cB + (size_t)(t + 2) * kstep;
;             const char* a3 = a2 + kstep; const char* b3 = b2 + kstep;
;             if (last && has_next) S.a_ready(nxt);
;             if constexpr (SP2) {
;             PG8_LDB(B0, 0, 0); PG8_LDB(B1, 0, 1); PG8_SCHED; PG8_LDA(At, 0, 0); PG8_STAGE(PG8_SA(1, 0), a1, voffA); PG8_STAGE(PG8_SA(1, 1), a1 + hstep, voffA);
;             PG8_WAIT_V(8); PG8_WAIT_L(0); PG8_BAR; PG8_MMA(0, 0, At, B0); PG8_MMA(0, 1, At, B1); PG8_BAR; PG8_SCHED;
;             PG8_LDA(At, 0, 1); PG8_STAGE(PG8_SB(0, 0), b2, voffB); PG8_STAGE(PG8_SB(0, 1), b2 + hstep, voffB);
;             PG8_WAIT_V(6); PG8_WAIT_L(0); PG8_BAR; PG8_MMA(1, 0, At, B0); PG8_MMA(1, 1, At, B1); PG8_BAR; PG8_SCHED;
.LBB0_426:
	s_add_u32 s44, s16, s88
	s_addc_u32 s45, s17, s89
	s_add_u32 s53, s44, 0x100
	s_addc_u32 s78, s45, 0
	s_add_u32 s44, s70, s88
	s_addc_u32 s45, s71, s89
	s_add_i32 s79, 0, 0x10000
	s_cmpk_eq_i32 s88, 0xf00
	s_cselect_b32 s45, s43, s45
	s_cselect_b32 s44, s69, s44
	s_cselect_b32 s95, s47, s78
	s_cselect_b32 s94, s68, s53
	s_add_i32 s53, 0, 0x14000
	v_add_u32_e32 v158, s79, v143
	v_add_u32_e32 v174, s53, v143
	ds_read_b128 v[146:149], v158
	ds_read_b128 v[150:153], v158 offset:1024
	ds_read_b128 v[154:157], v158 offset:2048
	ds_read_b128 v[158:161], v158 offset:3072
	ds_read_b128 v[162:165], v174
	ds_read_b128 v[166:169], v174 offset:1024
	ds_read_b128 v[170:173], v174 offset:2048
	ds_read_b128 v[174:177], v174 offset:3072
	v_lshl_add_u64 v[202:203], v[138:139], 0, s[88:89]
	v_lshl_add_u64 v[222:223], v[202:203], 0, s[26:27]
	s_add_i32 m0, s23, 0x8000
	ds_read_b128 v[178:181], v145
	ds_read_b128 v[182:185], v145 offset:1024
	ds_read_b128 v[186:189], v145 offset:2048
	ds_read_b128 v[190:193], v145 offset:3072
	ds_read_b128 v[194:197], v145 offset:4096
	ds_read_b128 v[198:201], v145 offset:5120
	ds_read_b128 v[206:209], v145 offset:6144
	ds_read_b128 v[218:221], v145 offset:7168
	global_load_lds_dwordx4 v[222:223], off
	v_lshl_add_u64 v[222:223], v[140:141], 0, s[88:89]
	v_lshl_add_u64 v[232:233], v[222:223], 0, s[26:27]
	s_add_i32 m0, s23, 0xa000
	v_lshl_add_u64 v[202:203], v[202:203], 0, s[28:29]
	global_load_lds_dwordx4 v[232:233], off
	s_add_i32 m0, s23, 0xc000
	s_nop 0
	global_load_lds_dwordx4 v[202:203], off
	v_lshl_add_u64 v[202:203], v[222:223], 0, s[28:29]
	s_add_i32 m0, s23, 0xe000
	s_nop 0
	global_load_lds_dwordx4 v[202:203], off
	s_waitcnt vmcnt(8)
	s_waitcnt lgkmcnt(0)
	s_barrier
	v_mfma_f32_16x16x32_bf16 v[124:127], v[146:149], v[178:181], v[124:127]
	v_mfma_f32_16x16x32_bf16 v[120:123], v[154:157], v[178:181], v[120:123]
	v_mfma_f32_16x16x32_bf16 v[116:119], v[146:149], v[186:189], v[116:119]
	v_mfma_f32_16x16x32_bf16 v[108:111], v[154:157], v[186:189], v[108:111]
	v_mfma_f32_16x16x32_bf16 v[100:103], v[146:149], v[194:197], v[100:103]
	v_mfma_f32_16x16x32_bf16 v[92:95], v[154:157], v[194:197], v[92:95]
	v_mfma_f32_16x16x32_bf16 v[84:87], v[146:149], v[206:209], v[84:87]
	v_mfma_f32_16x16x32_bf16 v[76:79], v[154:157], v[206:209], v[76:79]
	v_mfma_f32_16x16x32_bf16 v[124:127], v[150:153], v[182:185], v[124:127]
	v_mfma_f32_16x16x32_bf16 v[120:123], v[158:161], v[182:185], v[120:123]
	v_mfma_f32_16x16x32_bf16 v[116:119], v[150:153], v[190:193], v[116:119]
	v_mfma_f32_16x16x32_bf16 v[108:111], v[158:161], v[190:193], v[108:111]
	v_mfma_f32_16x16x32_bf16 v[100:103], v[150:153], v[198:201], v[100:103]
	v_mfma_f32_16x16x32_bf16 v[92:95], v[158:161], v[198:201], v[92:95]
	v_mfma_f32_16x16x32_bf16 v[84:87], v[150:153], v[218:221], v[84:87]
	v_mfma_f32_16x16x32_bf16 v[76:79], v[158:161], v[218:221], v[76:79]
	v_mfma_f32_16x16x32_bf16 v[112:115], v[162:165], v[178:181], v[112:115]
	v_mfma_f32_16x16x32_bf16 v[104:107], v[170:173], v[178:181], v[104:107]
	v_mfma_f32_16x16x32_bf16 v[96:99], v[162:165], v[186:189], v[96:99]
	v_mfma_f32_16x16x32_bf16 v[88:91], v[170:173], v[186:189], v[88:91]
	v_mfma_f32_16x16x32_bf16 v[80:83], v[162:165], v[194:197], v[80:83]
	v_mfma_f32_16x16x32_bf16 v[72:75], v[170:173], v[194:197], v[72:75]
	v_mfma_f32_16x16x32_bf16 v[68:71], v[162:165], v[206:209], v[68:71]
	v_mfma_f32_16x16x32_bf16 v[64:67], v[170:173], v[206:209], v[64:67]
	v_mfma_f32_16x16x32_bf16 v[112:115], v[166:169], v[182:185], v[112:115]
	v_mfma_f32_16x16x32_bf16 v[104:107], v[174:177], v[182:185], v[104:107]
	v_mfma_f32_16x16x32_bf16 v[96:99], v[166:169], v[190:193], v[96:99]
	v_mfma_f32_16x16x32_bf16 v[88:91], v[174:177], v[190:193], v[88:91]
	v_mfma_f32_16x16x32_bf16 v[80:83], v[166:169], v[198:201], v[80:83]
	v_mfma_f32_16x16x32_bf16 v[72:75], v[174:177], v[198:201], v[72:75]
	v_mfma_f32_16x16x32_bf16 v[68:71], v[166:169], v[218:221], v[68:71]
	v_mfma_f32_16x16x32_bf16 v[64:67], v[174:177], v[218:221], v[64:67]
	s_barrier
	s_add_i32 s78, s79, s22
	v_lshl_add_u64 v[202:203], s[44:45], 0, v[204:205]
	s_mov_b32 m0, s78
	ds_read_b128 v[178:181], v145 offset:16384
	ds_read_b128 v[182:185], v145 offset:17408
	ds_read_b128 v[186:189], v145 offset:18432
	ds_read_b128 v[190:193], v145 offset:19456
	ds_read_b128 v[194:197], v145 offset:20480
	ds_read_b128 v[198:201], v145 offset:21504
	ds_read_b128 v[206:209], v145 offset:22528
	ds_read_b128 v[218:221], v145 offset:23552
	global_load_lds_dwordx4 v[202:203], off
	s_add_i32 m0, s78, 0x2000
	s_add_u32 s78, s44, 0x80000
	v_lshl_add_u64 v[222:223], s[44:45], 0, v[128:129]
	s_addc_u32 s79, s45, 0
	s_add_i32 s53, s53, s22
	global_load_lds_dwordx4 v[222:223], off
	v_lshl_add_u64 v[232:233], s[78:79], 0, v[204:205]
	s_mov_b32 m0, s53
	s_nop 0
	global_load_lds_dwordx4 v[232:233], off
	v_lshl_add_u64 v[232:233], s[78:79], 0, v[128:129]
	s_add_i32 m0, s53, 0x2000
	s_nop 0
	global_load_lds_dwordx4 v[232:233], off
	s_waitcnt vmcnt(6)
	s_waitcnt lgkmcnt(0)
	s_nop 0
	s_barrier
; #define PG8_MMA(ai, bj, At, Bt) do { __builtin_amdgcn_s_setprio(1); _Pragma("unroll") for (int m = 0; m < 4; ++m) _Pragma("unroll") for (int n = 0; n < 2; ++n) _Pragma("unroll") for (int k = 0; k < 2; ++k) \
;         acc[ai][bj][m][n] = __builtin_amdgcn_mfma_f32_16x16x32_bf16(Bt[n][k], At[m][k], acc[ai][bj][m][n], 0, 0, 0); __builtin_amdgcn_s_setprio(0); } while (0)
; #define PG8_WAIT_V(n) asm volatile("s_waitcnt vmcnt(" #n ")" ::: "memory")
; #define PG8_WAIT_L(n) asm volatile("s_waitcnt lgkmcnt(" #n ")" ::: "memory")
; #define PG8_BAR __builtin_amdgcn_s_barrier()
; #define PG8_SCHED __builtin_amdgcn_sched_barrier(0)
; template <class Epi, class Sched, bool ALIGN_EPI = false, bool SP2 = false>
; __device__ __forceinline__ void gemm_phase(PG8_LAS unsigned char* lds, const Gemm g, const Sched& S, const Epi& E) {
;     ...
;             PG8_WAIT_V(6); PG8_WAIT_L(0); PG8_BAR; PG8_MMA(1, 0, At, B0); PG8_MMA(1, 1, At, B1); PG8_BAR; PG8_SCHED;
	v_mfma_f32_16x16x32_bf16 v[60:63], v[146:149], v[178:181], v[60:63]
	v_mfma_f32_16x16x32_bf16 v[56:59], v[154:157], v[178:181], v[56:59]
	v_mfma_f32_16x16x32_bf16 v[52:55], v[146:149], v[186:189], v[52:55]
	v_mfma_f32_16x16x32_bf16 v[44:47], v[154:157], v[186:189], v[44:47]
	v_mfma_f32_16x16x32_bf16 v[36:39], v[146:149], v[194:197], v[36:39]
	v_mfma_f32_16x16x32_bf16 v[28:31], v[154:157], v[194:197], v[28:31]
	v_mfma_f32_16x16x32_bf16 v[20:23], v[146:149], v[206:209], v[20:23]
	v_mfma_f32_16x16x32_bf16 v[12:15], v[154:157], v[206:209], v[12:15]
	v_mfma_f32_16x16x32_bf16 v[60:63], v[150:153], v[182:185], v[60:63]
	v_mfma_f32_16x16x32_bf16 v[56:59], v[158:161], v[182:185], v[56:59]
	v_mfma_f32_16x16x32_bf16 v[52:55], v[150:153], v[190:193], v[52:55]
	v_mfma_f32_16x16x32_bf16 v[44:47], v[158:161], v[190:193], v[44:47]
	v_mfma_f32_16x16x32_bf16 v[36:39], v[150:153], v[198:201], v[36:39]
	v_mfma_f32_16x16x32_bf16 v[28:31], v[158:161], v[198:201], v[28:31]
	v_mfma_f32_16x16x32_bf16 v[20:23], v[150:153], v[218:221], v[20:23]
	v_mfma_f32_16x16x32_bf16 v[12:15], v[158:161], v[218:221], v[12:15]
	v_mfma_f32_16x16x32_bf16 v[48:51], v[162:165], v[178:181], v[48:51]
	v_mfma_f32_16x16x32_bf16 v[40:43], v[170:173], v[178:181], v[40:43]
	v_mfma_f32_16x16x32_bf16 v[32:35], v[162:165], v[186:189], v[32:35]
	v_mfma_f32_16x16x32_bf16 v[24:27], v[170:173], v[186:189], v[24:27]
	v_mfma_f32_16x16x32_bf16 v[16:19], v[162:165], v[194:197], v[16:19]
	v_mfma_f32_16x16x32_bf16 v[8:11], v[170:173], v[194:197], v[8:11]
	v_mfma_f32_16x16x32_bf16 v[4:7], v[162:165], v[206:209], v[4:7]
	v_mfma_f32_16x16x32_bf16 v[0:3], v[170:173], v[206:209], v[0:3]
	v_mfma_f32_16x16x32_bf16 v[48:51], v[166:169], v[182:185], v[48:51]
	v_mfma_f32_16x16x32_bf16 v[40:43], v[174:177], v[182:185], v[40:43]
	v_mfma_f32_16x16x32_bf16 v[32:35], v[166:169], v[190:193], v[32:35]
	v_mfma_f32_16x16x32_bf16 v[24:27], v[174:177], v[190:193], v[24:27]
	v_mfma_f32_16x16x32_bf16 v[16:19], v[166:169], v[198:201], v[16:19]
	v_mfma_f32_16x16x32_bf16 v[8:11], v[174:177], v[198:201], v[8:11]
	v_mfma_f32_16x16x32_bf16 v[4:7], v[166:169], v[218:221], v[4:7]
	v_mfma_f32_16x16x32_bf16 v[0:3], v[174:177], v[218:221], v[0:3]
	s_barrier
; #define PG8_STAGE(bufoff, gbase, voff) do { _Pragma("unroll") for (int _i = 0; _i < 2; ++_i) \
;         __builtin_amdgcn_global_load_lds((const unsigned*)((const char*)(gbase) + (voff)[_i]), (PG8_LAS unsigned*)(lds + (bufoff) + ldsw + _i * 8192), 16, 0, 0); } while (0)
; #define PG8_LDA(dst, b, h) do { _Pragma("unroll") for (int m = 0; m < 4; ++m) _Pragma("unroll") for (int k = 0; k < 2; ++k) dst[m][k] = *(const PG8_LAS bf16x8*)(lds + PG8_SA(b, h) + aoff + m * 2048 + k * 1024); } while (0)
; #define PG8_LDB(dst, b, h) do { _Pragma("unroll") for (int n = 0; n < 2; ++n) _Pragma("unroll") for (int k = 0; k < 2; ++k) dst[n][k] = *(const PG8_LAS bf16x8*)(lds + PG8_SB(b, h) + boff + n * 2048 + k * 1024); } while (0)
; #define PG8_MMA(ai, bj, At, Bt) do { __builtin_amdgcn_s_setprio(1); _Pragma("unroll") for (int m = 0; m < 4; ++m) _Pragma("unroll") for (int n = 0; n < 2; ++n) _Pragma("unroll") for (int k = 0; k < 2; ++k) \
;         acc[ai][bj][m][n] = __builtin_amdgcn_mfma_f32_16x16x32_bf16(Bt[n][k], At[m][k], acc[ai][bj][m][n], 0, 0, 0); __builtin_amdgcn_s_setprio(0); } while (0)
; #define PG8_WAIT_V(n) asm volatile("s_waitcnt vmcnt(" #n ")" ::: "memory")
; #define PG8_WAIT_L(n) asm volatile("s_waitcnt lgkmcnt(" #n ")" ::: "memory")
; #define PG8_BAR __builtin_amdgcn_s_barrier()
; #define PG8_SCHED __builtin_amdgcn_sched_barrier(0)
; template <class Epi, class Sched, bool ALIGN_EPI = false, bool SP2 = false>
; __device__ __forceinline__ void gemm_phase(PG8_LAS unsigned char* lds, const Gemm g, const Sched& S, const Epi& E) {
;     ...
;             PG8_LDB(B0, 1, 0); PG8_LDB(B1, 1, 1); PG8_SCHED; PG8_LDA(At, 1, 0); PG8_STAGE(PG8_SA(0, 0), a2, voffA); PG8_STAGE(PG8_SA(0, 1), a2 + hstep, voffA);
;             PG8_WAIT_V(8); PG8_WAIT_L(0); PG8_BAR; PG8_MMA(0, 0, At, B0); PG8_MMA(0, 1, At, B1); PG8_BAR; PG8_SCHED;
;             PG8_LDA(At, 1, 1); PG8_STAGE(PG8_SB(1, 0), b3, voffB); PG8_STAGE(PG8_SB(1, 1), b3 + hstep, voffB); (void)a3;
;             PG8_WAIT_V(6); PG8_WAIT_L(0); PG8_BAR; PG8_MMA(1, 0, At, B0); PG8_MMA(1, 1, At, B1); PG8_BAR; PG8_SCHED;
.Lpl_o:
	s_add_i32 s53, 0, 0x18000
	s_add_i32 s84, 0, 0x1c000
	v_add_u32_e32 v158, s53, v143
	v_add_u32_e32 v174, s84, v143
	ds_read_b128 v[146:149], v158
	ds_read_b128 v[150:153], v158 offset:1024
	ds_read_b128 v[154:157], v158 offset:2048
	ds_read_b128 v[158:161], v158 offset:3072
	ds_read_b128 v[162:165], v174
	ds_read_b128 v[166:169], v174 offset:1024
	ds_read_b128 v[170:173], v174 offset:2048
	ds_read_b128 v[174:177], v174 offset:3072
	s_mov_b32 m0, s23
	v_lshl_add_u64 v[232:233], s[94:95], 0, v[132:133]
	s_add_u32 s78, s94, 0x80000
	ds_read_b128 v[178:181], v145 offset:32768
	ds_read_b128 v[182:185], v145 offset:33792
	ds_read_b128 v[186:189], v145 offset:34816
	ds_read_b128 v[190:193], v145 offset:35840
	ds_read_b128 v[194:197], v145 offset:36864
	ds_read_b128 v[198:201], v145 offset:37888
	ds_read_b128 v[206:209], v145 offset:38912
	ds_read_b128 v[218:221], v145 offset:39936
	global_load_lds_dwordx4 v[232:233], off
	v_lshl_add_u64 v[232:233], s[94:95], 0, v[130:131]
	s_mov_b32 m0, s34
	s_addc_u32 s79, s95, 0
	global_load_lds_dwordx4 v[232:233], off
	v_lshl_add_u64 v[232:233], s[78:79], 0, v[132:133]
	s_mov_b32 m0, s35
	s_nop 0
	global_load_lds_dwordx4 v[232:233], off
	v_lshl_add_u64 v[232:233], s[78:79], 0, v[130:131]
	s_mov_b32 m0, s36
	s_nop 0
	global_load_lds_dwordx4 v[232:233], off
	s_waitcnt vmcnt(8)
	s_waitcnt lgkmcnt(0)
	s_nop 0
	s_barrier
	v_mfma_f32_16x16x32_bf16 v[124:127], v[146:149], v[178:181], v[124:127]
	v_mfma_f32_16x16x32_bf16 v[120:123], v[154:157], v[178:181], v[120:123]
	v_mfma_f32_16x16x32_bf16 v[116:119], v[146:149], v[186:189], v[116:119]
	v_mfma_f32_16x16x32_bf16 v[108:111], v[154:157], v[186:189], v[108:111]
	v_mfma_f32_16x16x32_bf16 v[100:103], v[146:149], v[194:197], v[100:103]
	v_mfma_f32_16x16x32_bf16 v[92:95], v[154:157], v[194:197], v[92:95]
	v_mfma_f32_16x16x32_bf16 v[84:87], v[146:149], v[206:209], v[84:87]
	v_mfma_f32_16x16x32_bf16 v[76:79], v[154:157], v[206:209], v[76:79]
	v_mfma_f32_16x16x32_bf16 v[124:127], v[150:153], v[182:185], v[124:127]
	v_mfma_f32_16x16x32_bf16 v[120:123], v[158:161], v[182:185], v[120:123]
	v_mfma_f32_16x16x32_bf16 v[116:119], v[150:153], v[190:193], v[116:119]
	v_mfma_f32_16x16x32_bf16 v[108:111], v[158:161], v[190:193], v[108:111]
	v_mfma_f32_16x16x32_bf16 v[100:103], v[150:153], v[198:201], v[100:103]
	v_mfma_f32_16x16x32_bf16 v[92:95], v[158:161], v[198:201], v[92:95]
	v_mfma_f32_16x16x32_bf16 v[84:87], v[150:153], v[218:221], v[84:87]
	v_mfma_f32_16x16x32_bf16 v[76:79], v[158:161], v[218:221], v[76:79]
	v_mfma_f32_16x16x32_bf16 v[112:115], v[162:165], v[178:181], v[112:115]
	v_mfma_f32_16x16x32_bf16 v[104:107], v[170:173], v[178:181], v[104:107]
	v_mfma_f32_16x16x32_bf16 v[96:99], v[162:165], v[186:189], v[96:99]
	v_mfma_f32_16x16x32_bf16 v[88:91], v[170:173], v[186:189], v[88:91]
	v_mfma_f32_16x16x32_bf16 v[80:83], v[162:165], v[194:197], v[80:83]
	v_mfma_f32_16x16x32_bf16 v[72:75], v[170:173], v[194:197], v[72:75]
	v_mfma_f32_16x16x32_bf16 v[68:71], v[162:165], v[206:209], v[68:71]
	v_mfma_f32_16x16x32_bf16 v[64:67], v[170:173], v[206:209], v[64:67]
	v_mfma_f32_16x16x32_bf16 v[112:115], v[166:169], v[182:185], v[112:115]
	v_mfma_f32_16x16x32_bf16 v[104:107], v[174:177], v[182:185], v[104:107]
	v_mfma_f32_16x16x32_bf16 v[96:99], v[166:169], v[190:193], v[96:99]
	v_mfma_f32_16x16x32_bf16 v[88:91], v[174:177], v[190:193], v[88:91]
	v_mfma_f32_16x16x32_bf16 v[80:83], v[166:169], v[198:201], v[80:83]
	v_mfma_f32_16x16x32_bf16 v[72:75], v[174:177], v[198:201], v[72:75]
	v_mfma_f32_16x16x32_bf16 v[68:71], v[166:169], v[218:221], v[68:71]
	v_mfma_f32_16x16x32_bf16 v[64:67], v[174:177], v[218:221], v[64:67]
	s_barrier
	s_add_i32 s53, s53, s22
	v_lshl_add_u64 v[202:203], v[202:203], 0, s[26:27]
	s_mov_b32 m0, s53
	ds_read_b128 v[178:181], v145 offset:49152
	ds_read_b128 v[182:185], v145 offset:50176
	ds_read_b128 v[186:189], v145 offset:51200
	ds_read_b128 v[190:193], v145 offset:52224
	ds_read_b128 v[194:197], v145 offset:53248
	ds_read_b128 v[198:201], v145 offset:54272
	ds_read_b128 v[206:209], v145 offset:55296
	ds_read_b128 v[218:221], v145 offset:56320
	global_load_lds_dwordx4 v[202:203], off
	s_add_i32 m0, s53, 0x2000
	s_add_u32 s44, s44, 0x80080
	v_lshl_add_u64 v[202:203], v[222:223], 0, s[26:27]
	s_addc_u32 s45, s45, 0
	s_add_i32 s53, s84, s22
	global_load_lds_dwordx4 v[202:203], off
	v_lshl_add_u64 v[202:203], s[44:45], 0, v[204:205]
	s_mov_b32 m0, s53
	s_nop 0
	global_load_lds_dwordx4 v[202:203], off
	v_lshl_add_u64 v[202:203], s[44:45], 0, v[128:129]
	s_add_i32 m0, s53, 0x2000
	s_nop 0
	global_load_lds_dwordx4 v[202:203], off
	s_waitcnt vmcnt(6)
	s_waitcnt lgkmcnt(0)
	s_nop 0
	s_barrier
	v_mfma_f32_16x16x32_bf16 v[60:63], v[146:149], v[178:181], v[60:63]
	v_mfma_f32_16x16x32_bf16 v[56:59], v[154:157], v[178:181], v[56:59]
	v_mfma_f32_16x16x32_bf16 v[52:55], v[146:149], v[186:189], v[52:55]
	v_mfma_f32_16x16x32_bf16 v[44:47], v[154:157], v[186:189], v[44:47]
	v_mfma_f32_16x16x32_bf16 v[36:39], v[146:149], v[194:197], v[36:39]
	v_mfma_f32_16x16x32_bf16 v[28:31], v[154:157], v[194:197], v[28:31]
	v_mfma_f32_16x16x32_bf16 v[20:23], v[146:149], v[206:209], v[20:23]
	v_mfma_f32_16x16x32_bf16 v[12:15], v[154:157], v[206:209], v[12:15]
	v_mfma_f32_16x16x32_bf16 v[60:63], v[150:153], v[182:185], v[60:63]
	v_mfma_f32_16x16x32_bf16 v[56:59], v[158:161], v[182:185], v[56:59]
	v_mfma_f32_16x16x32_bf16 v[52:55], v[150:153], v[190:193], v[52:55]
	v_mfma_f32_16x16x32_bf16 v[44:47], v[158:161], v[190:193], v[44:47]
	v_mfma_f32_16x16x32_bf16 v[36:39], v[150:153], v[198:201], v[36:39]
	v_mfma_f32_16x16x32_bf16 v[28:31], v[158:161], v[198:201], v[28:31]
	v_mfma_f32_16x16x32_bf16 v[20:23], v[150:153], v[218:221], v[20:23]
	v_mfma_f32_16x16x32_bf16 v[12:15], v[158:161], v[218:221], v[12:15]
	v_mfma_f32_16x16x32_bf16 v[48:51], v[162:165], v[178:181], v[48:51]
	v_mfma_f32_16x16x32_bf16 v[40:43], v[170:173], v[178:181], v[40:43]
	v_mfma_f32_16x16x32_bf16 v[32:35], v[162:165], v[186:189], v[32:35]
	v_mfma_f32_16x16x32_bf16 v[24:27], v[170:173], v[186:189], v[24:27]
	v_mfma_f32_16x16x32_bf16 v[16:19], v[162:165], v[194:197], v[16:19]
	v_mfma_f32_16x16x32_bf16 v[8:11], v[170:173], v[194:197], v[8:11]
	v_mfma_f32_16x16x32_bf16 v[4:7], v[162:165], v[206:209], v[4:7]
	v_mfma_f32_16x16x32_bf16 v[0:3], v[170:173], v[206:209], v[0:3]
	v_mfma_f32_16x16x32_bf16 v[48:51], v[166:169], v[182:185], v[48:51]
	v_mfma_f32_16x16x32_bf16 v[40:43], v[174:177], v[182:185], v[40:43]
	v_mfma_f32_16x16x32_bf16 v[32:35], v[166:169], v[190:193], v[32:35]
	v_mfma_f32_16x16x32_bf16 v[24:27], v[174:177], v[190:193], v[24:27]
	v_mfma_f32_16x16x32_bf16 v[16:19], v[166:169], v[198:201], v[16:19]
	v_mfma_f32_16x16x32_bf16 v[8:11], v[174:177], v[198:201], v[8:11]
	v_mfma_f32_16x16x32_bf16 v[4:7], v[166:169], v[218:221], v[4:7]
	v_mfma_f32_16x16x32_bf16 v[0:3], v[174:177], v[218:221], v[0:3]
	s_barrier
	s_add_i32 s52, s52, 2
	s_add_u32 s88, s88, 0x100
	s_addc_u32 s89, s89, 0
	s_cmp_gt_u32 s52, 29
	s_cbranch_scc0 .LBB0_426
	s_and_b64 vcc, exec, s[10:11]
	s_cbranch_vccz .LBB0_429
	s_barrier

; #define PG8_STAGE(bufoff, gbase, voff) do { _Pragma("unroll") for (int _i = 0; _i < 2; ++_i) \
;         __builtin_amdgcn_global_load_lds((const unsigned*)((const char*)(gbase) + (voff)[_i]), (PG8_LAS unsigned*)(lds + (bufoff) + ldsw + _i * 8192), 16, 0, 0); } while (0)
; #define PG8_LDA(dst, b, h) do { _Pragma("unroll") for (int m = 0; m < 4; ++m) _Pragma("unroll") for (int k = 0; k < 2; ++k) dst[m][k] = *(const PG8_LAS bf16x8*)(lds + PG8_SA(b, h) + aoff + m * 2048 + k * 1024); } while (0)
; #define PG8_LDB(dst, b, h) do { _Pragma("unroll") for (int n = 0; n < 2; ++n) _Pragma("unroll") for (int k = 0; k < 2; ++k) dst[n][k] = *(const PG8_LAS bf16x8*)(lds + PG8_SB(b, h) + boff + n * 2048 + k * 1024); } while (0)
; #define PG8_MMA(ai, bj, At, Bt) do { __builtin_amdgcn_s_setprio(1); _Pragma("unroll") for (int m = 0; m < 4; ++m) _Pragma("unroll") for (int n = 0; n < 2; ++n) _Pragma("unroll") for (int k = 0; k < 2; ++k) \
;         acc[ai][bj][m][n] = __builtin_amdgcn_mfma_f32_16x16x32_bf16(Bt[n][k], At[m][k], acc[ai][bj][m][n], 0, 0, 0); __builtin_amdgcn_s_setprio(0); } while (0)
; #define PG8_WAIT_V(n) asm volatile("s_waitcnt vmcnt(" #n ")" ::: "memory")
; #define PG8_WAIT_L(n) asm volatile("s_waitcnt lgkmcnt(" #n ")" ::: "memory")
; template <class Epi, class Sched, bool ALIGN_EPI = false, bool SP2 = false>
; __device__ __forceinline__ void gemm_phase(PG8_LAS unsigned char* lds, const Gemm g, const Sched& S, const Epi& E) {
;     ...
;             const bool last = (t == nt - 2);
;             const char* a1 = cA + (size_t)(t + 1) * kstep;
;             const char* a2 = last ? nA : cA + (size_t)(t + 2) * kstep; const char* b2 = last ? nB : cB + (size_t)(t + 2) * kstep;
;             const char* a3 = a2 + kstep; const char* b3 = b2 + kstep;
;             if (last && has_next) S.a_ready(nxt);
;             if constexpr (SP2) {
;             PG8_LDB(B0, 0, 0); PG8_LDB(B1, 0, 1); PG8_SCHED; PG8_LDA(At, 0, 0); PG8_STAGE(PG8_SA(1, 0), a1, voffA); PG8_STAGE(PG8_SA(1, 1), a1 + hstep, voffA);
;             PG8_WAIT_V(8); PG8_WAIT_L(0); PG8_BAR; PG8_MMA(0, 0, At, B0); PG8_MMA(0, 1, At, B1); PG8_BAR; PG8_SCHED;
;             PG8_LDA(At, 0, 1); PG8_STAGE(PG8_SB(0, 0), b2, voffB); PG8_STAGE(PG8_SB(0, 1), b2 + hstep, voffB);
;             PG8_WAIT_V(6); PG8_WAIT_L(0); PG8_BAR; PG8_MMA(1, 0, At, B0); PG8_MMA(1, 1, At, B1); PG8_BAR; PG8_SCHED;
.LBB0_605:
	s_add_u32 s10, s8, vcc_lo
	s_addc_u32 s11, s9, vcc_hi
	s_add_u32 s38, s10, 0x100
	s_addc_u32 s39, s11, 0
	s_add_u32 s10, s79, vcc_lo
	s_addc_u32 s11, s52, vcc_hi
	s_add_i32 s78, 0, 0x10000
	s_cmpk_eq_i32 vcc_lo, 0xf00
	s_cselect_b32 s11, s7, s11
	s_cselect_b32 s10, s71, s10
	s_cselect_b32 s69, s95, s39
	s_cselect_b32 s68, s70, s38
	s_add_i32 s92, 0, 0x14000
	v_add_u32_e32 v158, s78, v143
	v_add_u32_e32 v174, s92, v143
	ds_read_b128 v[146:149], v158
	ds_read_b128 v[150:153], v158 offset:1024
	ds_read_b128 v[154:157], v158 offset:2048
	ds_read_b128 v[158:161], v158 offset:3072
	ds_read_b128 v[162:165], v174
	ds_read_b128 v[166:169], v174 offset:1024
	ds_read_b128 v[170:173], v174 offset:2048
	ds_read_b128 v[174:177], v174 offset:3072
	v_lshl_add_u64 v[202:203], v[140:141], 0, vcc
	v_lshl_add_u64 v[222:223], v[202:203], 0, s[26:27]
	s_add_i32 m0, s37, 0x8000
	ds_read_b128 v[178:181], v145
	ds_read_b128 v[182:185], v145 offset:1024
	ds_read_b128 v[186:189], v145 offset:2048
	ds_read_b128 v[190:193], v145 offset:3072
	ds_read_b128 v[194:197], v145 offset:4096
	ds_read_b128 v[198:201], v145 offset:5120
	ds_read_b128 v[206:209], v145 offset:6144
	ds_read_b128 v[218:221], v145 offset:7168
	global_load_lds_dwordx4 v[222:223], off
	v_lshl_add_u64 v[222:223], v[138:139], 0, vcc
	v_lshl_add_u64 v[232:233], v[222:223], 0, s[26:27]
	s_add_i32 m0, s37, 0xa000
	v_lshl_add_u64 v[202:203], v[202:203], 0, s[28:29]
	global_load_lds_dwordx4 v[232:233], off
	s_add_i32 m0, s37, 0xc000
	s_nop 0
	global_load_lds_dwordx4 v[202:203], off
	v_lshl_add_u64 v[202:203], v[222:223], 0, s[28:29]
	s_add_i32 m0, s37, 0xe000
	s_nop 0
	global_load_lds_dwordx4 v[202:203], off
	s_waitcnt vmcnt(8)
	s_waitcnt lgkmcnt(0)
	s_barrier
	v_mfma_f32_16x16x32_bf16 v[124:127], v[146:149], v[178:181], v[124:127]
	v_mfma_f32_16x16x32_bf16 v[120:123], v[154:157], v[178:181], v[120:123]
	v_mfma_f32_16x16x32_bf16 v[108:111], v[146:149], v[186:189], v[108:111]
	v_mfma_f32_16x16x32_bf16 v[104:107], v[154:157], v[186:189], v[104:107]
	v_mfma_f32_16x16x32_bf16 v[92:95], v[146:149], v[194:197], v[92:95]
	v_mfma_f32_16x16x32_bf16 v[88:91], v[154:157], v[194:197], v[88:91]
	v_mfma_f32_16x16x32_bf16 v[76:79], v[146:149], v[206:209], v[76:79]
	v_mfma_f32_16x16x32_bf16 v[72:75], v[154:157], v[206:209], v[72:75]
	v_mfma_f32_16x16x32_bf16 v[124:127], v[150:153], v[182:185], v[124:127]
	v_mfma_f32_16x16x32_bf16 v[120:123], v[158:161], v[182:185], v[120:123]
	v_mfma_f32_16x16x32_bf16 v[108:111], v[150:153], v[190:193], v[108:111]
	v_mfma_f32_16x16x32_bf16 v[104:107], v[158:161], v[190:193], v[104:107]
	v_mfma_f32_16x16x32_bf16 v[92:95], v[150:153], v[198:201], v[92:95]
	v_mfma_f32_16x16x32_bf16 v[88:91], v[158:161], v[198:201], v[88:91]
	v_mfma_f32_16x16x32_bf16 v[76:79], v[150:153], v[218:221], v[76:79]
	v_mfma_f32_16x16x32_bf16 v[72:75], v[158:161], v[218:221], v[72:75]
	v_mfma_f32_16x16x32_bf16 v[116:119], v[162:165], v[178:181], v[116:119]
	v_mfma_f32_16x16x32_bf16 v[112:115], v[170:173], v[178:181], v[112:115]
	v_mfma_f32_16x16x32_bf16 v[100:103], v[162:165], v[186:189], v[100:103]
	v_mfma_f32_16x16x32_bf16 v[96:99], v[170:173], v[186:189], v[96:99]
	v_mfma_f32_16x16x32_bf16 v[84:87], v[162:165], v[194:197], v[84:87]
	v_mfma_f32_16x16x32_bf16 v[80:83], v[170:173], v[194:197], v[80:83]
	v_mfma_f32_16x16x32_bf16 v[68:71], v[162:165], v[206:209], v[68:71]
	v_mfma_f32_16x16x32_bf16 v[64:67], v[170:173], v[206:209], v[64:67]
	v_mfma_f32_16x16x32_bf16 v[116:119], v[166:169], v[182:185], v[116:119]
	v_mfma_f32_16x16x32_bf16 v[112:115], v[174:177], v[182:185], v[112:115]
	v_mfma_f32_16x16x32_bf16 v[100:103], v[166:169], v[190:193], v[100:103]
	v_mfma_f32_16x16x32_bf16 v[96:99], v[174:177], v[190:193], v[96:99]
	v_mfma_f32_16x16x32_bf16 v[84:87], v[166:169], v[198:201], v[84:87]
	v_mfma_f32_16x16x32_bf16 v[80:83], v[174:177], v[198:201], v[80:83]
	v_mfma_f32_16x16x32_bf16 v[68:71], v[166:169], v[218:221], v[68:71]
	v_mfma_f32_16x16x32_bf16 v[64:67], v[174:177], v[218:221], v[64:67]
	s_barrier
	s_add_i32 s38, s78, s36
	v_lshl_add_u64 v[202:203], s[10:11], 0, v[204:205]
	s_mov_b32 m0, s38
	ds_read_b128 v[178:181], v145 offset:16384
	ds_read_b128 v[182:185], v145 offset:17408
	ds_read_b128 v[186:189], v145 offset:18432
	ds_read_b128 v[190:193], v145 offset:19456
	ds_read_b128 v[194:197], v145 offset:20480
	ds_read_b128 v[198:201], v145 offset:21504
	ds_read_b128 v[206:209], v145 offset:22528
	ds_read_b128 v[218:221], v145 offset:23552
	global_load_lds_dwordx4 v[202:203], off
	s_add_i32 m0, s38, 0x2000
	s_add_u32 s38, s10, 0x80000
	v_lshl_add_u64 v[222:223], s[10:11], 0, v[128:129]
	s_addc_u32 s39, s11, 0
	s_add_i32 s78, s92, s36
	global_load_lds_dwordx4 v[222:223], off
	v_lshl_add_u64 v[232:233], s[38:39], 0, v[204:205]
	s_mov_b32 m0, s78
	s_nop 0
	global_load_lds_dwordx4 v[232:233], off
	v_lshl_add_u64 v[232:233], s[38:39], 0, v[128:129]
	s_add_i32 m0, s78, 0x2000
	s_nop 0
	global_load_lds_dwordx4 v[232:233], off
	s_waitcnt vmcnt(6)
	s_waitcnt lgkmcnt(0)
	s_nop 0
	s_barrier
; #define PG8_STAGE(bufoff, gbase, voff) do { _Pragma("unroll") for (int _i = 0; _i < 2; ++_i) \
;         __builtin_amdgcn_global_load_lds((const unsigned*)((const char*)(gbase) + (voff)[_i]), (PG8_LAS unsigned*)(lds + (bufoff) + ldsw + _i * 8192), 16, 0, 0); } while (0)
; #define PG8_LDA(dst, b, h) do { _Pragma("unroll") for (int m = 0; m < 4; ++m) _Pragma("unroll") for (int k = 0; k < 2; ++k) dst[m][k] = *(const PG8_LAS bf16x8*)(lds + PG8_SA(b, h) + aoff + m * 2048 + k * 1024); } while (0)
; #define PG8_LDB(dst, b, h) do { _Pragma("unroll") for (int n = 0; n < 2; ++n) _Pragma("unroll") for (int k = 0; k < 2; ++k) dst[n][k] = *(const PG8_LAS bf16x8*)(lds + PG8_SB(b, h) + boff + n * 2048 + k * 1024); } while (0)
; #define PG8_MMA(ai, bj, At, Bt) do { __builtin_amdgcn_s_setprio(1); _Pragma("unroll") for (int m = 0; m < 4; ++m) _Pragma("unroll") for (int n = 0; n < 2; ++n) _Pragma("unroll") for (int k = 0; k < 2; ++k) \
;         acc[ai][bj][m][n] = __builtin_amdgcn_mfma_f32_16x16x32_bf16(Bt[n][k], At[m][k], acc[ai][bj][m][n], 0, 0, 0); __builtin_amdgcn_s_setprio(0); } while (0)
; #define PG8_WAIT_V(n) asm volatile("s_waitcnt vmcnt(" #n ")" ::: "memory")
; #define PG8_WAIT_L(n) asm volatile("s_waitcnt lgkmcnt(" #n ")" ::: "memory")
; #define PG8_BAR __builtin_amdgcn_s_barrier()
; #define PG8_SCHED __builtin_amdgcn_sched_barrier(0)
; template <class Epi, class Sched, bool ALIGN_EPI = false, bool SP2 = false>
; __device__ __forceinline__ void gemm_phase(PG8_LAS unsigned char* lds, const Gemm g, const Sched& S, const Epi& E) {
;     ...
;             PG8_WAIT_V(6); PG8_WAIT_L(0); PG8_BAR; PG8_MMA(1, 0, At, B0); PG8_MMA(1, 1, At, B1); PG8_BAR; PG8_SCHED;
;             PG8_LDB(B0, 1, 0); PG8_LDB(B1, 1, 1); PG8_SCHED; PG8_LDA(At, 1, 0); PG8_STAGE(PG8_SA(0, 0), a2, voffA); PG8_STAGE(PG8_SA(0, 1), a2 + hstep, voffA);
;             PG8_WAIT_V(8); PG8_WAIT_L(0); PG8_BAR; PG8_MMA(0, 0, At, B0); PG8_MMA(0, 1, At, B1); PG8_BAR; PG8_SCHED;
	v_mfma_f32_16x16x32_bf16 v[60:63], v[146:149], v[178:181], v[60:63]
	v_mfma_f32_16x16x32_bf16 v[56:59], v[154:157], v[178:181], v[56:59]
	v_mfma_f32_16x16x32_bf16 v[44:47], v[146:149], v[186:189], v[44:47]
	v_mfma_f32_16x16x32_bf16 v[40:43], v[154:157], v[186:189], v[40:43]
	v_mfma_f32_16x16x32_bf16 v[28:31], v[146:149], v[194:197], v[28:31]
	v_mfma_f32_16x16x32_bf16 v[24:27], v[154:157], v[194:197], v[24:27]
	v_mfma_f32_16x16x32_bf16 v[12:15], v[146:149], v[206:209], v[12:15]
	v_mfma_f32_16x16x32_bf16 v[8:11], v[154:157], v[206:209], v[8:11]
	v_mfma_f32_16x16x32_bf16 v[60:63], v[150:153], v[182:185], v[60:63]
	v_mfma_f32_16x16x32_bf16 v[56:59], v[158:161], v[182:185], v[56:59]
	v_mfma_f32_16x16x32_bf16 v[44:47], v[150:153], v[190:193], v[44:47]
	v_mfma_f32_16x16x32_bf16 v[40:43], v[158:161], v[190:193], v[40:43]
	v_mfma_f32_16x16x32_bf16 v[28:31], v[150:153], v[198:201], v[28:31]
	v_mfma_f32_16x16x32_bf16 v[24:27], v[158:161], v[198:201], v[24:27]
	v_mfma_f32_16x16x32_bf16 v[12:15], v[150:153], v[218:221], v[12:15]
	v_mfma_f32_16x16x32_bf16 v[8:11], v[158:161], v[218:221], v[8:11]
	v_mfma_f32_16x16x32_bf16 v[52:55], v[162:165], v[178:181], v[52:55]
	v_mfma_f32_16x16x32_bf16 v[48:51], v[170:173], v[178:181], v[48:51]
	v_mfma_f32_16x16x32_bf16 v[36:39], v[162:165], v[186:189], v[36:39]
	v_mfma_f32_16x16x32_bf16 v[32:35], v[170:173], v[186:189], v[32:35]
	v_mfma_f32_16x16x32_bf16 v[20:23], v[162:165], v[194:197], v[20:23]
	v_mfma_f32_16x16x32_bf16 v[16:19], v[170:173], v[194:197], v[16:19]
	v_mfma_f32_16x16x32_bf16 v[4:7], v[162:165], v[206:209], v[4:7]
	v_mfma_f32_16x16x32_bf16 v[0:3], v[170:173], v[206:209], v[0:3]
	v_mfma_f32_16x16x32_bf16 v[52:55], v[166:169], v[182:185], v[52:55]
	v_mfma_f32_16x16x32_bf16 v[48:51], v[174:177], v[182:185], v[48:51]
	v_mfma_f32_16x16x32_bf16 v[36:39], v[166:169], v[190:193], v[36:39]
	v_mfma_f32_16x16x32_bf16 v[32:35], v[174:177], v[190:193], v[32:35]
	v_mfma_f32_16x16x32_bf16 v[20:23], v[166:169], v[198:201], v[20:23]
	v_mfma_f32_16x16x32_bf16 v[16:19], v[174:177], v[198:201], v[16:19]
	v_mfma_f32_16x16x32_bf16 v[4:7], v[166:169], v[218:221], v[4:7]
	v_mfma_f32_16x16x32_bf16 v[0:3], v[174:177], v[218:221], v[0:3]
	s_barrier
.Lpl_up:
	s_add_i32 s78, 0, 0x18000
	s_add_i32 s92, 0, 0x1c000
	v_add_u32_e32 v158, s78, v143
	v_add_u32_e32 v174, s92, v143
	ds_read_b128 v[146:149], v158
	ds_read_b128 v[150:153], v158 offset:1024
	ds_read_b128 v[154:157], v158 offset:2048
	ds_read_b128 v[158:161], v158 offset:3072
	ds_read_b128 v[162:165], v174
	ds_read_b128 v[166:169], v174 offset:1024
	ds_read_b128 v[170:173], v174 offset:2048
	ds_read_b128 v[174:177], v174 offset:3072
	s_mov_b32 m0, s37
	v_lshl_add_u64 v[232:233], s[68:69], 0, v[132:133]
	s_add_u32 s38, s68, 0x80000
	ds_read_b128 v[178:181], v145 offset:32768
	ds_read_b128 v[182:185], v145 offset:33792
	ds_read_b128 v[186:189], v145 offset:34816
	ds_read_b128 v[190:193], v145 offset:35840
	ds_read_b128 v[194:197], v145 offset:36864
	ds_read_b128 v[198:201], v145 offset:37888
	ds_read_b128 v[206:209], v145 offset:38912
	ds_read_b128 v[218:221], v145 offset:39936
	global_load_lds_dwordx4 v[232:233], off
	v_lshl_add_u64 v[232:233], s[68:69], 0, v[130:131]
	s_mov_b32 m0, s57
	s_addc_u32 s39, s69, 0
	global_load_lds_dwordx4 v[232:233], off
	v_lshl_add_u64 v[232:233], s[38:39], 0, v[132:133]
	s_mov_b32 m0, s75
	s_nop 0
	global_load_lds_dwordx4 v[232:233], off
	v_lshl_add_u64 v[232:233], s[38:39], 0, v[130:131]
	s_mov_b32 m0, s84
	s_nop 0
	global_load_lds_dwordx4 v[232:233], off
	s_waitcnt vmcnt(8)
	s_waitcnt lgkmcnt(0)
	s_nop 0
	s_barrier
; #define PG8_STAGE(bufoff, gbase, voff) do { _Pragma("unroll") for (int _i = 0; _i < 2; ++_i) \
;         __builtin_amdgcn_global_load_lds((const unsigned*)((const char*)(gbase) + (voff)[_i]), (PG8_LAS unsigned*)(lds + (bufoff) + ldsw + _i * 8192), 16, 0, 0); } while (0)
; #define PG8_LDA(dst, b, h) do { _Pragma("unroll") for (int m = 0; m < 4; ++m) _Pragma("unroll") for (int k = 0; k < 2; ++k) dst[m][k] = *(const PG8_LAS bf16x8*)(lds + PG8_SA(b, h) + aoff + m * 2048 + k * 1024); } while (0)
; #define PG8_MMA(ai, bj, At, Bt) do { __builtin_amdgcn_s_setprio(1); _Pragma("unroll") for (int m = 0; m < 4; ++m) _Pragma("unroll") for (int n = 0; n < 2; ++n) _Pragma("unroll") for (int k = 0; k < 2; ++k) \
;         acc[ai][bj][m][n] = __builtin_amdgcn_mfma_f32_16x16x32_bf16(Bt[n][k], At[m][k], acc[ai][bj][m][n], 0, 0, 0); __builtin_amdgcn_s_setprio(0); } while (0)
; #define PG8_WAIT_V(n) asm volatile("s_waitcnt vmcnt(" #n ")" ::: "memory")
; #define PG8_WAIT_L(n) asm volatile("s_waitcnt lgkmcnt(" #n ")" ::: "memory")
; #define PG8_BAR __builtin_amdgcn_s_barrier()
; #define PG8_SCHED __builtin_amdgcn_sched_barrier(0)
; template <class Epi, class Sched, bool ALIGN_EPI = false, bool SP2 = false>
; __device__ __forceinline__ void gemm_phase(PG8_LAS unsigned char* lds, const Gemm g, const Sched& S, const Epi& E) {
;     ...
;             PG8_WAIT_V(8); PG8_WAIT_L(0); PG8_BAR; PG8_MMA(0, 0, At, B0); PG8_MMA(0, 1, At, B1); PG8_BAR; PG8_SCHED;
;             PG8_LDA(At, 1, 1); PG8_STAGE(PG8_SB(1, 0), b3, voffB); PG8_STAGE(PG8_SB(1, 1), b3 + hstep, voffB); (void)a3;
;             PG8_WAIT_V(6); PG8_WAIT_L(0); PG8_BAR; PG8_MMA(1, 0, At, B0); PG8_MMA(1, 1, At, B1); PG8_BAR; PG8_SCHED;
	v_mfma_f32_16x16x32_bf16 v[124:127], v[146:149], v[178:181], v[124:127]
	v_mfma_f32_16x16x32_bf16 v[120:123], v[154:157], v[178:181], v[120:123]
	v_mfma_f32_16x16x32_bf16 v[108:111], v[146:149], v[186:189], v[108:111]
	v_mfma_f32_16x16x32_bf16 v[104:107], v[154:157], v[186:189], v[104:107]
	v_mfma_f32_16x16x32_bf16 v[92:95], v[146:149], v[194:197], v[92:95]
	v_mfma_f32_16x16x32_bf16 v[88:91], v[154:157], v[194:197], v[88:91]
	v_mfma_f32_16x16x32_bf16 v[76:79], v[146:149], v[206:209], v[76:79]
	v_mfma_f32_16x16x32_bf16 v[72:75], v[154:157], v[206:209], v[72:75]
	v_mfma_f32_16x16x32_bf16 v[124:127], v[150:153], v[182:185], v[124:127]
	v_mfma_f32_16x16x32_bf16 v[120:123], v[158:161], v[182:185], v[120:123]
	v_mfma_f32_16x16x32_bf16 v[108:111], v[150:153], v[190:193], v[108:111]
	v_mfma_f32_16x16x32_bf16 v[104:107], v[158:161], v[190:193], v[104:107]
	v_mfma_f32_16x16x32_bf16 v[92:95], v[150:153], v[198:201], v[92:95]
	v_mfma_f32_16x16x32_bf16 v[88:91], v[158:161], v[198:201], v[88:91]
	v_mfma_f32_16x16x32_bf16 v[76:79], v[150:153], v[218:221], v[76:79]
	v_mfma_f32_16x16x32_bf16 v[72:75], v[158:161], v[218:221], v[72:75]
	v_mfma_f32_16x16x32_bf16 v[116:119], v[162:165], v[178:181], v[116:119]
	v_mfma_f32_16x16x32_bf16 v[112:115], v[170:173], v[178:181], v[112:115]
	v_mfma_f32_16x16x32_bf16 v[100:103], v[162:165], v[186:189], v[100:103]
	v_mfma_f32_16x16x32_bf16 v[96:99], v[170:173], v[186:189], v[96:99]
	v_mfma_f32_16x16x32_bf16 v[84:87], v[162:165], v[194:197], v[84:87]
	v_mfma_f32_16x16x32_bf16 v[80:83], v[170:173], v[194:197], v[80:83]
	v_mfma_f32_16x16x32_bf16 v[68:71], v[162:165], v[206:209], v[68:71]
	v_mfma_f32_16x16x32_bf16 v[64:67], v[170:173], v[206:209], v[64:67]
	v_mfma_f32_16x16x32_bf16 v[116:119], v[166:169], v[182:185], v[116:119]
	v_mfma_f32_16x16x32_bf16 v[112:115], v[174:177], v[182:185], v[112:115]
	v_mfma_f32_16x16x32_bf16 v[100:103], v[166:169], v[190:193], v[100:103]
	v_mfma_f32_16x16x32_bf16 v[96:99], v[174:177], v[190:193], v[96:99]
	v_mfma_f32_16x16x32_bf16 v[84:87], v[166:169], v[198:201], v[84:87]
	v_mfma_f32_16x16x32_bf16 v[80:83], v[174:177], v[198:201], v[80:83]
	v_mfma_f32_16x16x32_bf16 v[68:71], v[166:169], v[218:221], v[68:71]
	v_mfma_f32_16x16x32_bf16 v[64:67], v[174:177], v[218:221], v[64:67]
	s_barrier
	s_add_i32 s38, s78, s36
	v_lshl_add_u64 v[202:203], v[202:203], 0, s[26:27]
	s_mov_b32 m0, s38
	ds_read_b128 v[178:181], v145 offset:49152
	ds_read_b128 v[182:185], v145 offset:50176
	ds_read_b128 v[186:189], v145 offset:51200
	ds_read_b128 v[190:193], v145 offset:52224
	ds_read_b128 v[194:197], v145 offset:53248
	ds_read_b128 v[198:201], v145 offset:54272
	ds_read_b128 v[206:209], v145 offset:55296
	ds_read_b128 v[218:221], v145 offset:56320
	global_load_lds_dwordx4 v[202:203], off
	s_add_i32 m0, s38, 0x2000
	s_add_u32 s10, s10, 0x80080
	v_lshl_add_u64 v[202:203], v[222:223], 0, s[26:27]
	s_addc_u32 s11, s11, 0
	s_add_i32 s38, s92, s36
	global_load_lds_dwordx4 v[202:203], off
	v_lshl_add_u64 v[202:203], s[10:11], 0, v[204:205]
	s_mov_b32 m0, s38
	s_nop 0
	global_load_lds_dwordx4 v[202:203], off
	v_lshl_add_u64 v[202:203], s[10:11], 0, v[128:129]
	s_add_i32 m0, s38, 0x2000
	s_nop 0
	global_load_lds_dwordx4 v[202:203], off
	s_waitcnt vmcnt(6)
	s_waitcnt lgkmcnt(0)
	s_nop 0
	s_barrier
	v_mfma_f32_16x16x32_bf16 v[60:63], v[146:149], v[178:181], v[60:63]
	v_mfma_f32_16x16x32_bf16 v[56:59], v[154:157], v[178:181], v[56:59]
	v_mfma_f32_16x16x32_bf16 v[44:47], v[146:149], v[186:189], v[44:47]
	v_mfma_f32_16x16x32_bf16 v[40:43], v[154:157], v[186:189], v[40:43]
	v_mfma_f32_16x16x32_bf16 v[28:31], v[146:149], v[194:197], v[28:31]
	v_mfma_f32_16x16x32_bf16 v[24:27], v[154:157], v[194:197], v[24:27]
	v_mfma_f32_16x16x32_bf16 v[12:15], v[146:149], v[206:209], v[12:15]
	v_mfma_f32_16x16x32_bf16 v[8:11], v[154:157], v[206:209], v[8:11]
	v_mfma_f32_16x16x32_bf16 v[60:63], v[150:153], v[182:185], v[60:63]
	v_mfma_f32_16x16x32_bf16 v[56:59], v[158:161], v[182:185], v[56:59]
	v_mfma_f32_16x16x32_bf16 v[44:47], v[150:153], v[190:193], v[44:47]
	v_mfma_f32_16x16x32_bf16 v[40:43], v[158:161], v[190:193], v[40:43]
	v_mfma_f32_16x16x32_bf16 v[28:31], v[150:153], v[198:201], v[28:31]
	v_mfma_f32_16x16x32_bf16 v[24:27], v[158:161], v[198:201], v[24:27]
	v_mfma_f32_16x16x32_bf16 v[12:15], v[150:153], v[218:221], v[12:15]
	v_mfma_f32_16x16x32_bf16 v[8:11], v[158:161], v[218:221], v[8:11]
	v_mfma_f32_16x16x32_bf16 v[52:55], v[162:165], v[178:181], v[52:55]
	v_mfma_f32_16x16x32_bf16 v[48:51], v[170:173], v[178:181], v[48:51]
	v_mfma_f32_16x16x32_bf16 v[36:39], v[162:165], v[186:189], v[36:39]
	v_mfma_f32_16x16x32_bf16 v[32:35], v[170:173], v[186:189], v[32:35]
	v_mfma_f32_16x16x32_bf16 v[20:23], v[162:165], v[194:197], v[20:23]
	v_mfma_f32_16x16x32_bf16 v[16:19], v[170:173], v[194:197], v[16:19]
	v_mfma_f32_16x16x32_bf16 v[4:7], v[162:165], v[206:209], v[4:7]
	v_mfma_f32_16x16x32_bf16 v[0:3], v[170:173], v[206:209], v[0:3]
	v_mfma_f32_16x16x32_bf16 v[52:55], v[166:169], v[182:185], v[52:55]
	v_mfma_f32_16x16x32_bf16 v[48:51], v[174:177], v[182:185], v[48:51]
	v_mfma_f32_16x16x32_bf16 v[36:39], v[166:169], v[190:193], v[36:39]
	v_mfma_f32_16x16x32_bf16 v[32:35], v[174:177], v[190:193], v[32:35]
	v_mfma_f32_16x16x32_bf16 v[20:23], v[166:169], v[198:201], v[20:23]
	v_mfma_f32_16x16x32_bf16 v[16:19], v[174:177], v[198:201], v[16:19]
	v_mfma_f32_16x16x32_bf16 v[4:7], v[166:169], v[218:221], v[4:7]
	v_mfma_f32_16x16x32_bf16 v[0:3], v[174:177], v[218:221], v[0:3]
	s_barrier
	s_add_i32 s53, s53, 2
	s_add_u32 vcc_lo, vcc_lo, 0x100
	s_addc_u32 vcc_hi, vcc_hi, 0
	s_cmp_gt_u32 s53, 29
	s_cbranch_scc0 .LBB0_605
	s_and_b64 vcc, exec, s[4:5]
	s_cbranch_vccz .LBB0_608
	s_barrier

; #define PG8_STAGE(bufoff, gbase, voff) do { _Pragma("unroll") for (int _i = 0; _i < 2; ++_i) \
;         __builtin_amdgcn_global_load_lds((const unsigned*)((const char*)(gbase) + (voff)[_i]), (PG8_LAS unsigned*)(lds + (bufoff) + ldsw + _i * 8192), 16, 0, 0); } while (0)
; #define PG8_LDA(dst, b, h) do { _Pragma("unroll") for (int m = 0; m < 4; ++m) _Pragma("unroll") for (int k = 0; k < 2; ++k) dst[m][k] = *(const PG8_LAS bf16x8*)(lds + PG8_SA(b, h) + aoff + m * 2048 + k * 1024); } while (0)
; #define PG8_LDB(dst, b, h) do { _Pragma("unroll") for (int n = 0; n < 2; ++n) _Pragma("unroll") for (int k = 0; k < 2; ++k) dst[n][k] = *(const PG8_LAS bf16x8*)(lds + PG8_SB(b, h) + boff + n * 2048 + k * 1024); } while (0)
; #define PG8_MMA(ai, bj, At, Bt) do { __builtin_amdgcn_s_setprio(1); _Pragma("unroll") for (int m = 0; m < 4; ++m) _Pragma("unroll") for (int n = 0; n < 2; ++n) _Pragma("unroll") for (int k = 0; k < 2; ++k) \
;         acc[ai][bj][m][n] = __builtin_amdgcn_mfma_f32_16x16x32_bf16(Bt[n][k], At[m][k], acc[ai][bj][m][n], 0, 0, 0); __builtin_amdgcn_s_setprio(0); } while (0)
; #define PG8_WAIT_V(n) asm volatile("s_waitcnt vmcnt(" #n ")" ::: "memory")
; #define PG8_WAIT_L(n) asm volatile("s_waitcnt lgkmcnt(" #n ")" ::: "memory")
; template <class Epi, class Sched, bool ALIGN_EPI = false, bool SP2 = false>
; __device__ __forceinline__ void gemm_phase(PG8_LAS unsigned char* lds, const Gemm g, const Sched& S, const Epi& E) {
;     ...
;             const bool last = (t == nt - 2);
;             const char* a1 = cA + (size_t)(t + 1) * kstep;
;             const char* a2 = last ? nA : cA + (size_t)(t + 2) * kstep; const char* b2 = last ? nB : cB + (size_t)(t + 2) * kstep;
;             const char* a3 = a2 + kstep; const char* b3 = b2 + kstep;
;             if (last && has_next) S.a_ready(nxt);
;             if constexpr (SP2) {
;             PG8_LDB(B0, 0, 0); PG8_LDB(B1, 0, 1); PG8_SCHED; PG8_LDA(At, 0, 0); PG8_STAGE(PG8_SA(1, 0), a1, voffA); PG8_STAGE(PG8_SA(1, 1), a1 + hstep, voffA);
;             PG8_WAIT_V(8); PG8_WAIT_L(0); PG8_BAR; PG8_MMA(0, 0, At, B0); PG8_MMA(0, 1, At, B1); PG8_BAR; PG8_SCHED;
;             PG8_LDA(At, 0, 1); PG8_STAGE(PG8_SB(0, 0), b2, voffB); PG8_STAGE(PG8_SB(0, 1), b2 + hstep, voffB);
;             PG8_WAIT_V(6); PG8_WAIT_L(0); PG8_BAR; PG8_MMA(1, 0, At, B0); PG8_MMA(1, 1, At, B1); PG8_BAR; PG8_SCHED;
.LBB0_702:
	s_add_u32 s38, s16, s88
	s_addc_u32 s39, s17, s89
	s_add_u32 s38, s38, 0x100
	s_addc_u32 s39, s39, 0
	s_add_u32 s44, s97, s88
	s_addc_u32 s45, vcc_lo, s89
	s_add_i32 s53, 0, 0x10000
	s_cmpk_eq_i32 s88, 0x3f00
	s_cselect_b32 s45, s43, s45
	s_cselect_b32 s44, s71, s44
	s_cselect_b32 s69, s47, s39
	s_cselect_b32 s68, s70, s38
	s_add_i32 s78, 0, 0x14000
	v_add_u32_e32 v158, s53, v143
	v_add_u32_e32 v174, s78, v143
	ds_read_b128 v[146:149], v158
	ds_read_b128 v[150:153], v158 offset:1024
	ds_read_b128 v[154:157], v158 offset:2048
	ds_read_b128 v[158:161], v158 offset:3072
	ds_read_b128 v[162:165], v174
	ds_read_b128 v[166:169], v174 offset:1024
	ds_read_b128 v[170:173], v174 offset:2048
	ds_read_b128 v[174:177], v174 offset:3072
	v_lshl_add_u64 v[202:203], v[138:139], 0, s[88:89]
	v_lshl_add_u64 v[222:223], v[202:203], 0, s[26:27]
	s_add_i32 m0, s36, 0x8000
	ds_read_b128 v[178:181], v145
	ds_read_b128 v[182:185], v145 offset:1024
	ds_read_b128 v[186:189], v145 offset:2048
	ds_read_b128 v[190:193], v145 offset:3072
	ds_read_b128 v[194:197], v145 offset:4096
	ds_read_b128 v[198:201], v145 offset:5120
	ds_read_b128 v[206:209], v145 offset:6144
	ds_read_b128 v[218:221], v145 offset:7168
	global_load_lds_dwordx4 v[222:223], off
	v_lshl_add_u64 v[222:223], v[140:141], 0, s[88:89]
	v_lshl_add_u64 v[232:233], v[222:223], 0, s[26:27]
	s_add_i32 m0, s36, 0xa000
	v_lshl_add_u64 v[202:203], v[202:203], 0, s[90:91]
	global_load_lds_dwordx4 v[232:233], off
	s_add_i32 m0, s36, 0xc000
	s_nop 0
	global_load_lds_dwordx4 v[202:203], off
	v_lshl_add_u64 v[202:203], v[222:223], 0, s[90:91]
	s_add_i32 m0, s36, 0xe000
	s_nop 0
	global_load_lds_dwordx4 v[202:203], off
	s_waitcnt vmcnt(8)
	s_waitcnt lgkmcnt(0)
	s_barrier
	v_mfma_f32_16x16x32_bf16 v[124:127], v[146:149], v[178:181], v[124:127]
	v_mfma_f32_16x16x32_bf16 v[120:123], v[154:157], v[178:181], v[120:123]
	v_mfma_f32_16x16x32_bf16 v[116:119], v[146:149], v[186:189], v[116:119]
	v_mfma_f32_16x16x32_bf16 v[108:111], v[154:157], v[186:189], v[108:111]
	v_mfma_f32_16x16x32_bf16 v[100:103], v[146:149], v[194:197], v[100:103]
	v_mfma_f32_16x16x32_bf16 v[92:95], v[154:157], v[194:197], v[92:95]
	v_mfma_f32_16x16x32_bf16 v[84:87], v[146:149], v[206:209], v[84:87]
	v_mfma_f32_16x16x32_bf16 v[76:79], v[154:157], v[206:209], v[76:79]
	v_mfma_f32_16x16x32_bf16 v[124:127], v[150:153], v[182:185], v[124:127]
	v_mfma_f32_16x16x32_bf16 v[120:123], v[158:161], v[182:185], v[120:123]
	v_mfma_f32_16x16x32_bf16 v[116:119], v[150:153], v[190:193], v[116:119]
	v_mfma_f32_16x16x32_bf16 v[108:111], v[158:161], v[190:193], v[108:111]
	v_mfma_f32_16x16x32_bf16 v[100:103], v[150:153], v[198:201], v[100:103]
	v_mfma_f32_16x16x32_bf16 v[92:95], v[158:161], v[198:201], v[92:95]
	v_mfma_f32_16x16x32_bf16 v[84:87], v[150:153], v[218:221], v[84:87]
	v_mfma_f32_16x16x32_bf16 v[76:79], v[158:161], v[218:221], v[76:79]
	v_mfma_f32_16x16x32_bf16 v[112:115], v[162:165], v[178:181], v[112:115]
	v_mfma_f32_16x16x32_bf16 v[104:107], v[170:173], v[178:181], v[104:107]
	v_mfma_f32_16x16x32_bf16 v[96:99], v[162:165], v[186:189], v[96:99]
	v_mfma_f32_16x16x32_bf16 v[88:91], v[170:173], v[186:189], v[88:91]
	v_mfma_f32_16x16x32_bf16 v[80:83], v[162:165], v[194:197], v[80:83]
	v_mfma_f32_16x16x32_bf16 v[72:75], v[170:173], v[194:197], v[72:75]
	v_mfma_f32_16x16x32_bf16 v[68:71], v[162:165], v[206:209], v[68:71]
	v_mfma_f32_16x16x32_bf16 v[64:67], v[170:173], v[206:209], v[64:67]
	v_mfma_f32_16x16x32_bf16 v[112:115], v[166:169], v[182:185], v[112:115]
	v_mfma_f32_16x16x32_bf16 v[104:107], v[174:177], v[182:185], v[104:107]
	v_mfma_f32_16x16x32_bf16 v[96:99], v[166:169], v[190:193], v[96:99]
	v_mfma_f32_16x16x32_bf16 v[88:91], v[174:177], v[190:193], v[88:91]
	v_mfma_f32_16x16x32_bf16 v[80:83], v[166:169], v[198:201], v[80:83]
	v_mfma_f32_16x16x32_bf16 v[72:75], v[174:177], v[198:201], v[72:75]
	v_mfma_f32_16x16x32_bf16 v[68:71], v[166:169], v[218:221], v[68:71]
	v_mfma_f32_16x16x32_bf16 v[64:67], v[174:177], v[218:221], v[64:67]
	s_barrier
	s_add_i32 s38, s53, s35
	v_lshl_add_u64 v[202:203], s[44:45], 0, v[204:205]
	s_mov_b32 m0, s38
	ds_read_b128 v[178:181], v145 offset:16384
	ds_read_b128 v[182:185], v145 offset:17408
	ds_read_b128 v[186:189], v145 offset:18432
	ds_read_b128 v[190:193], v145 offset:19456
	ds_read_b128 v[194:197], v145 offset:20480
	ds_read_b128 v[198:201], v145 offset:21504
	ds_read_b128 v[206:209], v145 offset:22528
	ds_read_b128 v[218:221], v145 offset:23552
	global_load_lds_dwordx4 v[202:203], off
	s_add_i32 m0, s38, 0x2000
	s_add_u32 s38, s44, 0x200000
	v_lshl_add_u64 v[222:223], s[44:45], 0, v[128:129]
	s_addc_u32 s39, s45, 0
	s_add_i32 s53, s78, s35
	global_load_lds_dwordx4 v[222:223], off
	v_lshl_add_u64 v[232:233], s[38:39], 0, v[204:205]
	s_mov_b32 m0, s53
	s_nop 0
	global_load_lds_dwordx4 v[232:233], off
	v_lshl_add_u64 v[232:233], s[38:39], 0, v[128:129]
	s_add_i32 m0, s53, 0x2000
	s_nop 0
	global_load_lds_dwordx4 v[232:233], off
	s_waitcnt vmcnt(6)
	s_waitcnt lgkmcnt(0)
	s_nop 0
	s_barrier
; #define PG8_MMA(ai, bj, At, Bt) do { __builtin_amdgcn_s_setprio(1); _Pragma("unroll") for (int m = 0; m < 4; ++m) _Pragma("unroll") for (int n = 0; n < 2; ++n) _Pragma("unroll") for (int k = 0; k < 2; ++k) \
;         acc[ai][bj][m][n] = __builtin_amdgcn_mfma_f32_16x16x32_bf16(Bt[n][k], At[m][k], acc[ai][bj][m][n], 0, 0, 0); __builtin_amdgcn_s_setprio(0); } while (0)
; #define PG8_WAIT_V(n) asm volatile("s_waitcnt vmcnt(" #n ")" ::: "memory")
; #define PG8_WAIT_L(n) asm volatile("s_waitcnt lgkmcnt(" #n ")" ::: "memory")
; #define PG8_BAR __builtin_amdgcn_s_barrier()
; #define PG8_SCHED __builtin_amdgcn_sched_barrier(0)
; template <class Epi, class Sched, bool ALIGN_EPI = false, bool SP2 = false>
; __device__ __forceinline__ void gemm_phase(PG8_LAS unsigned char* lds, const Gemm g, const Sched& S, const Epi& E) {
;     ...
;             PG8_WAIT_V(6); PG8_WAIT_L(0); PG8_BAR; PG8_MMA(1, 0, At, B0); PG8_MMA(1, 1, At, B1); PG8_BAR; PG8_SCHED;
	v_mfma_f32_16x16x32_bf16 v[60:63], v[146:149], v[178:181], v[60:63]
	v_mfma_f32_16x16x32_bf16 v[56:59], v[154:157], v[178:181], v[56:59]
	v_mfma_f32_16x16x32_bf16 v[52:55], v[146:149], v[186:189], v[52:55]
	v_mfma_f32_16x16x32_bf16 v[44:47], v[154:157], v[186:189], v[44:47]
	v_mfma_f32_16x16x32_bf16 v[36:39], v[146:149], v[194:197], v[36:39]
	v_mfma_f32_16x16x32_bf16 v[28:31], v[154:157], v[194:197], v[28:31]
	v_mfma_f32_16x16x32_bf16 v[20:23], v[146:149], v[206:209], v[20:23]
	v_mfma_f32_16x16x32_bf16 v[12:15], v[154:157], v[206:209], v[12:15]
	v_mfma_f32_16x16x32_bf16 v[60:63], v[150:153], v[182:185], v[60:63]
	v_mfma_f32_16x16x32_bf16 v[56:59], v[158:161], v[182:185], v[56:59]
	v_mfma_f32_16x16x32_bf16 v[52:55], v[150:153], v[190:193], v[52:55]
	v_mfma_f32_16x16x32_bf16 v[44:47], v[158:161], v[190:193], v[44:47]
	v_mfma_f32_16x16x32_bf16 v[36:39], v[150:153], v[198:201], v[36:39]
	v_mfma_f32_16x16x32_bf16 v[28:31], v[158:161], v[198:201], v[28:31]
	v_mfma_f32_16x16x32_bf16 v[20:23], v[150:153], v[218:221], v[20:23]
	v_mfma_f32_16x16x32_bf16 v[12:15], v[158:161], v[218:221], v[12:15]
	v_mfma_f32_16x16x32_bf16 v[48:51], v[162:165], v[178:181], v[48:51]
	v_mfma_f32_16x16x32_bf16 v[40:43], v[170:173], v[178:181], v[40:43]
	v_mfma_f32_16x16x32_bf16 v[32:35], v[162:165], v[186:189], v[32:35]
	v_mfma_f32_16x16x32_bf16 v[24:27], v[170:173], v[186:189], v[24:27]
	v_mfma_f32_16x16x32_bf16 v[16:19], v[162:165], v[194:197], v[16:19]
	v_mfma_f32_16x16x32_bf16 v[8:11], v[170:173], v[194:197], v[8:11]
	v_mfma_f32_16x16x32_bf16 v[4:7], v[162:165], v[206:209], v[4:7]
	v_mfma_f32_16x16x32_bf16 v[0:3], v[170:173], v[206:209], v[0:3]
	v_mfma_f32_16x16x32_bf16 v[48:51], v[166:169], v[182:185], v[48:51]
	v_mfma_f32_16x16x32_bf16 v[40:43], v[174:177], v[182:185], v[40:43]
	v_mfma_f32_16x16x32_bf16 v[32:35], v[166:169], v[190:193], v[32:35]
	v_mfma_f32_16x16x32_bf16 v[24:27], v[174:177], v[190:193], v[24:27]
	v_mfma_f32_16x16x32_bf16 v[16:19], v[166:169], v[198:201], v[16:19]
	v_mfma_f32_16x16x32_bf16 v[8:11], v[174:177], v[198:201], v[8:11]
	v_mfma_f32_16x16x32_bf16 v[4:7], v[166:169], v[218:221], v[4:7]
	v_mfma_f32_16x16x32_bf16 v[0:3], v[174:177], v[218:221], v[0:3]
	s_barrier
; #define PG8_STAGE(bufoff, gbase, voff) do { _Pragma("unroll") for (int _i = 0; _i < 2; ++_i) \
;         __builtin_amdgcn_global_load_lds((const unsigned*)((const char*)(gbase) + (voff)[_i]), (PG8_LAS unsigned*)(lds + (bufoff) + ldsw + _i * 8192), 16, 0, 0); } while (0)
; #define PG8_LDA(dst, b, h) do { _Pragma("unroll") for (int m = 0; m < 4; ++m) _Pragma("unroll") for (int k = 0; k < 2; ++k) dst[m][k] = *(const PG8_LAS bf16x8*)(lds + PG8_SA(b, h) + aoff + m * 2048 + k * 1024); } while (0)
; #define PG8_LDB(dst, b, h) do { _Pragma("unroll") for (int n = 0; n < 2; ++n) _Pragma("unroll") for (int k = 0; k < 2; ++k) dst[n][k] = *(const PG8_LAS bf16x8*)(lds + PG8_SB(b, h) + boff + n * 2048 + k * 1024); } while (0)
; #define PG8_MMA(ai, bj, At, Bt) do { __builtin_amdgcn_s_setprio(1); _Pragma("unroll") for (int m = 0; m < 4; ++m) _Pragma("unroll") for (int n = 0; n < 2; ++n) _Pragma("unroll") for (int k = 0; k < 2; ++k) \
;         acc[ai][bj][m][n] = __builtin_amdgcn_mfma_f32_16x16x32_bf16(Bt[n][k], At[m][k], acc[ai][bj][m][n], 0, 0, 0); __builtin_amdgcn_s_setprio(0); } while (0)
; #define PG8_WAIT_V(n) asm volatile("s_waitcnt vmcnt(" #n ")" ::: "memory")
; #define PG8_WAIT_L(n) asm volatile("s_waitcnt lgkmcnt(" #n ")" ::: "memory")
; #define PG8_BAR __builtin_amdgcn_s_barrier()
; #define PG8_SCHED __builtin_amdgcn_sched_barrier(0)
; template <class Epi, class Sched, bool ALIGN_EPI = false, bool SP2 = false>
; __device__ __forceinline__ void gemm_phase(PG8_LAS unsigned char* lds, const Gemm g, const Sched& S, const Epi& E) {
;     ...
;             PG8_LDB(B0, 1, 0); PG8_LDB(B1, 1, 1); PG8_SCHED; PG8_LDA(At, 1, 0); PG8_STAGE(PG8_SA(0, 0), a2, voffA); PG8_STAGE(PG8_SA(0, 1), a2 + hstep, voffA);
;             PG8_WAIT_V(8); PG8_WAIT_L(0); PG8_BAR; PG8_MMA(0, 0, At, B0); PG8_MMA(0, 1, At, B1); PG8_BAR; PG8_SCHED;
;             PG8_LDA(At, 1, 1); PG8_STAGE(PG8_SB(1, 0), b3, voffB); PG8_STAGE(PG8_SB(1, 1), b3 + hstep, voffB); (void)a3;
;             PG8_WAIT_V(6); PG8_WAIT_L(0); PG8_BAR; PG8_MMA(1, 0, At, B0); PG8_MMA(1, 1, At, B1); PG8_BAR; PG8_SCHED;
.Lpl_down:
	s_add_i32 s53, 0, 0x18000
	s_add_i32 s78, 0, 0x1c000
	v_add_u32_e32 v158, s53, v143
	v_add_u32_e32 v174, s78, v143
	ds_read_b128 v[146:149], v158
	ds_read_b128 v[150:153], v158 offset:1024
	ds_read_b128 v[154:157], v158 offset:2048
	ds_read_b128 v[158:161], v158 offset:3072
	ds_read_b128 v[162:165], v174
	ds_read_b128 v[166:169], v174 offset:1024
	ds_read_b128 v[170:173], v174 offset:2048
	ds_read_b128 v[174:177], v174 offset:3072
	s_mov_b32 m0, s36
	v_lshl_add_u64 v[232:233], s[68:69], 0, v[132:133]
	s_add_u32 s38, s68, 0x200000
	ds_read_b128 v[178:181], v145 offset:32768
	ds_read_b128 v[182:185], v145 offset:33792
	ds_read_b128 v[186:189], v145 offset:34816
	ds_read_b128 v[190:193], v145 offset:35840
	ds_read_b128 v[194:197], v145 offset:36864
	ds_read_b128 v[198:201], v145 offset:37888
	ds_read_b128 v[206:209], v145 offset:38912
	ds_read_b128 v[218:221], v145 offset:39936
	global_load_lds_dwordx4 v[232:233], off
	v_lshl_add_u64 v[232:233], s[68:69], 0, v[130:131]
	s_mov_b32 m0, s37
	s_addc_u32 s39, s69, 0
	global_load_lds_dwordx4 v[232:233], off
	v_lshl_add_u64 v[232:233], s[38:39], 0, v[132:133]
	s_mov_b32 m0, s57
	s_nop 0
	global_load_lds_dwordx4 v[232:233], off
	v_lshl_add_u64 v[232:233], s[38:39], 0, v[130:131]
	s_mov_b32 m0, s75
	s_nop 0
	global_load_lds_dwordx4 v[232:233], off
	s_waitcnt vmcnt(8)
	s_waitcnt lgkmcnt(0)
	s_nop 0
	s_barrier
	v_mfma_f32_16x16x32_bf16 v[124:127], v[146:149], v[178:181], v[124:127]
	v_mfma_f32_16x16x32_bf16 v[120:123], v[154:157], v[178:181], v[120:123]
	v_mfma_f32_16x16x32_bf16 v[116:119], v[146:149], v[186:189], v[116:119]
	v_mfma_f32_16x16x32_bf16 v[108:111], v[154:157], v[186:189], v[108:111]
	v_mfma_f32_16x16x32_bf16 v[100:103], v[146:149], v[194:197], v[100:103]
	v_mfma_f32_16x16x32_bf16 v[92:95], v[154:157], v[194:197], v[92:95]
	v_mfma_f32_16x16x32_bf16 v[84:87], v[146:149], v[206:209], v[84:87]
	v_mfma_f32_16x16x32_bf16 v[76:79], v[154:157], v[206:209], v[76:79]
	v_mfma_f32_16x16x32_bf16 v[124:127], v[150:153], v[182:185], v[124:127]
	v_mfma_f32_16x16x32_bf16 v[120:123], v[158:161], v[182:185], v[120:123]
	v_mfma_f32_16x16x32_bf16 v[116:119], v[150:153], v[190:193], v[116:119]
	v_mfma_f32_16x16x32_bf16 v[108:111], v[158:161], v[190:193], v[108:111]
	v_mfma_f32_16x16x32_bf16 v[100:103], v[150:153], v[198:201], v[100:103]
	v_mfma_f32_16x16x32_bf16 v[92:95], v[158:161], v[198:201], v[92:95]
	v_mfma_f32_16x16x32_bf16 v[84:87], v[150:153], v[218:221], v[84:87]
	v_mfma_f32_16x16x32_bf16 v[76:79], v[158:161], v[218:221], v[76:79]
	v_mfma_f32_16x16x32_bf16 v[112:115], v[162:165], v[178:181], v[112:115]
	v_mfma_f32_16x16x32_bf16 v[104:107], v[170:173], v[178:181], v[104:107]
	v_mfma_f32_16x16x32_bf16 v[96:99], v[162:165], v[186:189], v[96:99]
	v_mfma_f32_16x16x32_bf16 v[88:91], v[170:173], v[186:189], v[88:91]
	v_mfma_f32_16x16x32_bf16 v[80:83], v[162:165], v[194:197], v[80:83]
	v_mfma_f32_16x16x32_bf16 v[72:75], v[170:173], v[194:197], v[72:75]
	v_mfma_f32_16x16x32_bf16 v[68:71], v[162:165], v[206:209], v[68:71]
	v_mfma_f32_16x16x32_bf16 v[64:67], v[170:173], v[206:209], v[64:67]
	v_mfma_f32_16x16x32_bf16 v[112:115], v[166:169], v[182:185], v[112:115]
	v_mfma_f32_16x16x32_bf16 v[104:107], v[174:177], v[182:185], v[104:107]
	v_mfma_f32_16x16x32_bf16 v[96:99], v[166:169], v[190:193], v[96:99]
	v_mfma_f32_16x16x32_bf16 v[88:91], v[174:177], v[190:193], v[88:91]
	v_mfma_f32_16x16x32_bf16 v[80:83], v[166:169], v[198:201], v[80:83]
	v_mfma_f32_16x16x32_bf16 v[72:75], v[174:177], v[198:201], v[72:75]
	v_mfma_f32_16x16x32_bf16 v[68:71], v[166:169], v[218:221], v[68:71]
	v_mfma_f32_16x16x32_bf16 v[64:67], v[174:177], v[218:221], v[64:67]
	s_barrier
	s_add_i32 s38, s53, s35
	v_lshl_add_u64 v[202:203], v[202:203], 0, s[26:27]
	s_mov_b32 m0, s38
	ds_read_b128 v[178:181], v145 offset:49152
	ds_read_b128 v[182:185], v145 offset:50176
	ds_read_b128 v[186:189], v145 offset:51200
	ds_read_b128 v[190:193], v145 offset:52224
	ds_read_b128 v[194:197], v145 offset:53248
	ds_read_b128 v[198:201], v145 offset:54272
	ds_read_b128 v[206:209], v145 offset:55296
	ds_read_b128 v[218:221], v145 offset:56320
	global_load_lds_dwordx4 v[202:203], off
	s_add_i32 m0, s38, 0x2000
	s_add_u32 s38, s44, 0x200080
	v_lshl_add_u64 v[202:203], v[222:223], 0, s[26:27]
	s_addc_u32 s39, s45, 0
	s_add_i32 s44, s78, s35
	global_load_lds_dwordx4 v[202:203], off
	v_lshl_add_u64 v[202:203], s[38:39], 0, v[204:205]
	s_mov_b32 m0, s44
	s_nop 0
	global_load_lds_dwordx4 v[202:203], off
	v_lshl_add_u64 v[202:203], s[38:39], 0, v[128:129]
	s_add_i32 m0, s44, 0x2000
	s_nop 0
	global_load_lds_dwordx4 v[202:203], off
	s_waitcnt vmcnt(6)
	s_waitcnt lgkmcnt(0)
	s_nop 0
	s_barrier
	v_mfma_f32_16x16x32_bf16 v[60:63], v[146:149], v[178:181], v[60:63]
	v_mfma_f32_16x16x32_bf16 v[56:59], v[154:157], v[178:181], v[56:59]
	v_mfma_f32_16x16x32_bf16 v[52:55], v[146:149], v[186:189], v[52:55]
	v_mfma_f32_16x16x32_bf16 v[44:47], v[154:157], v[186:189], v[44:47]
	v_mfma_f32_16x16x32_bf16 v[36:39], v[146:149], v[194:197], v[36:39]
	v_mfma_f32_16x16x32_bf16 v[28:31], v[154:157], v[194:197], v[28:31]
	v_mfma_f32_16x16x32_bf16 v[20:23], v[146:149], v[206:209], v[20:23]
	v_mfma_f32_16x16x32_bf16 v[12:15], v[154:157], v[206:209], v[12:15]
	v_mfma_f32_16x16x32_bf16 v[60:63], v[150:153], v[182:185], v[60:63]
	v_mfma_f32_16x16x32_bf16 v[56:59], v[158:161], v[182:185], v[56:59]
	v_mfma_f32_16x16x32_bf16 v[52:55], v[150:153], v[190:193], v[52:55]
	v_mfma_f32_16x16x32_bf16 v[44:47], v[158:161], v[190:193], v[44:47]
	v_mfma_f32_16x16x32_bf16 v[36:39], v[150:153], v[198:201], v[36:39]
	v_mfma_f32_16x16x32_bf16 v[28:31], v[158:161], v[198:201], v[28:31]
	v_mfma_f32_16x16x32_bf16 v[20:23], v[150:153], v[218:221], v[20:23]
	v_mfma_f32_16x16x32_bf16 v[12:15], v[158:161], v[218:221], v[12:15]
	v_mfma_f32_16x16x32_bf16 v[48:51], v[162:165], v[178:181], v[48:51]
	v_mfma_f32_16x16x32_bf16 v[40:43], v[170:173], v[178:181], v[40:43]
	v_mfma_f32_16x16x32_bf16 v[32:35], v[162:165], v[186:189], v[32:35]
	v_mfma_f32_16x16x32_bf16 v[24:27], v[170:173], v[186:189], v[24:27]
	v_mfma_f32_16x16x32_bf16 v[16:19], v[162:165], v[194:197], v[16:19]
	v_mfma_f32_16x16x32_bf16 v[8:11], v[170:173], v[194:197], v[8:11]
	v_mfma_f32_16x16x32_bf16 v[4:7], v[162:165], v[206:209], v[4:7]
	v_mfma_f32_16x16x32_bf16 v[0:3], v[170:173], v[206:209], v[0:3]
	v_mfma_f32_16x16x32_bf16 v[48:51], v[166:169], v[182:185], v[48:51]
	v_mfma_f32_16x16x32_bf16 v[40:43], v[174:177], v[182:185], v[40:43]
	v_mfma_f32_16x16x32_bf16 v[32:35], v[166:169], v[190:193], v[32:35]
	v_mfma_f32_16x16x32_bf16 v[24:27], v[174:177], v[190:193], v[24:27]
	v_mfma_f32_16x16x32_bf16 v[16:19], v[166:169], v[198:201], v[16:19]
	v_mfma_f32_16x16x32_bf16 v[8:11], v[174:177], v[198:201], v[8:11]
	v_mfma_f32_16x16x32_bf16 v[4:7], v[166:169], v[218:221], v[4:7]
	v_mfma_f32_16x16x32_bf16 v[0:3], v[174:177], v[218:221], v[0:3]
	s_barrier
	s_add_i32 s52, s52, 2
	s_add_u32 s88, s88, 0x100
	s_addc_u32 s89, s89, 0
	s_cmpk_gt_u32 s52, 0x7d
	s_cbranch_scc0 .LBB0_702
	s_and_b64 vcc, exec, s[10:11]
	s_cbranch_vccz .LBB0_705
	s_barrier
